# GEMM compute segments: no momentary priority drop between the two 16-MFMA blocks (on top of diff-loop changes)
# baseline (speedup 1.0000x reference)
.LBB0_46:
	s_add_u32 s26, s22, 0x100
	s_addc_u32 s27, s23, 0
	s_add_i32 s0, 0, 0x10000
	s_cmp_eq_u32 s46, 40
	s_cselect_b32 s67, s9, s27
	s_cselect_b32 s66, s8, s26
	s_cselect_b32 s31, s19, s38
	s_cselect_b32 s30, s18, s1
	s_add_i32 s33, 0, 0x14000
	v_add_u32_e32 v76, s0, v157
	v_add_u32_e32 v154, s33, v157
	ds_read_b128 v[64:67], v76
	ds_read_b128 v[68:71], v76 offset:1024
	ds_read_b128 v[72:75], v76 offset:2048
	ds_read_b128 v[76:79], v76 offset:3072
	ds_read_b128 v[150:153], v154
	ds_read_b128 v[160:163], v154 offset:1024
	ds_read_b128 v[164:167], v154 offset:2048
	ds_read_b128 v[168:171], v154 offset:3072
	v_lshl_add_u64 v[154:155], s[22:23], 0, v[146:147]
	s_add_i32 m0, s69, 0xc000
	ds_read_b128 v[172:175], v159
	ds_read_b128 v[176:179], v159 offset:1024
	ds_read_b128 v[180:183], v159 offset:2048
	ds_read_b128 v[184:187], v159 offset:3072
	ds_read_b128 v[188:191], v159 offset:4096
	ds_read_b128 v[194:197], v159 offset:5120
	ds_read_b128 v[202:205], v159 offset:6144
	ds_read_b128 v[206:209], v159 offset:7168
	global_load_lds_dwordx4 v[154:155], off
	v_lshl_add_u64 v[154:155], s[22:23], 0, v[148:149]
	s_add_i32 m0, s69, 0xe000
	s_nop 0
	global_load_lds_dwordx4 v[154:155], off
	s_waitcnt vmcnt(8)
	s_waitcnt lgkmcnt(0)
	s_barrier
	s_setprio 1
	s_waitcnt lgkmcnt(0)
	v_mfma_f32_16x16x32_bf16 v[140:143], v[64:67], v[172:175], v[140:143]
	v_mfma_f32_16x16x32_bf16 v[136:139], v[72:75], v[172:175], v[136:139]
	v_mfma_f32_16x16x32_bf16 v[132:135], v[64:67], v[180:183], v[132:135]
	v_mfma_f32_16x16x32_bf16 v[128:131], v[72:75], v[180:183], v[128:131]
	v_mfma_f32_16x16x32_bf16 v[108:111], v[64:67], v[188:191], v[108:111]
	v_mfma_f32_16x16x32_bf16 v[104:107], v[72:75], v[188:191], v[104:107]
	v_mfma_f32_16x16x32_bf16 v[100:103], v[64:67], v[202:205], v[100:103]
	v_mfma_f32_16x16x32_bf16 v[96:99], v[72:75], v[202:205], v[96:99]
	v_mfma_f32_16x16x32_bf16 v[140:143], v[68:71], v[176:179], v[140:143]
	v_mfma_f32_16x16x32_bf16 v[136:139], v[76:79], v[176:179], v[136:139]
	v_mfma_f32_16x16x32_bf16 v[132:135], v[68:71], v[184:187], v[132:135]
	v_mfma_f32_16x16x32_bf16 v[128:131], v[76:79], v[184:187], v[128:131]
	v_mfma_f32_16x16x32_bf16 v[108:111], v[68:71], v[194:197], v[108:111]
	v_mfma_f32_16x16x32_bf16 v[104:107], v[76:79], v[194:197], v[104:107]
	v_mfma_f32_16x16x32_bf16 v[100:103], v[68:71], v[206:209], v[100:103]
	v_mfma_f32_16x16x32_bf16 v[96:99], v[76:79], v[206:209], v[96:99]
	v_mfma_f32_16x16x32_bf16 v[124:127], v[150:153], v[172:175], v[124:127]
	v_mfma_f32_16x16x32_bf16 v[120:123], v[164:167], v[172:175], v[120:123]
	v_mfma_f32_16x16x32_bf16 v[116:119], v[150:153], v[180:183], v[116:119]
	v_mfma_f32_16x16x32_bf16 v[112:115], v[164:167], v[180:183], v[112:115]
	v_mfma_f32_16x16x32_bf16 v[92:95], v[150:153], v[188:191], v[92:95]
	v_mfma_f32_16x16x32_bf16 v[88:91], v[164:167], v[188:191], v[88:91]
	v_mfma_f32_16x16x32_bf16 v[84:87], v[150:153], v[202:205], v[84:87]
	v_mfma_f32_16x16x32_bf16 v[80:83], v[164:167], v[202:205], v[80:83]
	v_mfma_f32_16x16x32_bf16 v[124:127], v[160:163], v[176:179], v[124:127]
	v_mfma_f32_16x16x32_bf16 v[120:123], v[168:171], v[176:179], v[120:123]
	v_mfma_f32_16x16x32_bf16 v[116:119], v[160:163], v[184:187], v[116:119]
	v_mfma_f32_16x16x32_bf16 v[112:115], v[168:171], v[184:187], v[112:115]
	v_mfma_f32_16x16x32_bf16 v[92:95], v[160:163], v[194:197], v[92:95]
	v_mfma_f32_16x16x32_bf16 v[88:91], v[168:171], v[194:197], v[88:91]
	v_mfma_f32_16x16x32_bf16 v[84:87], v[160:163], v[206:209], v[84:87]
	v_mfma_f32_16x16x32_bf16 v[80:83], v[168:171], v[206:209], v[80:83]
	s_setprio 0
	s_barrier
	s_add_i32 s0, s0, s68
	v_lshl_add_u64 v[154:155], s[30:31], 0, v[192:193]
	s_mov_b32 m0, s0
	ds_read_b128 v[172:175], v159 offset:16384
	ds_read_b128 v[176:179], v159 offset:17408
	ds_read_b128 v[180:183], v159 offset:18432
	ds_read_b128 v[184:187], v159 offset:19456
	ds_read_b128 v[188:191], v159 offset:20480
	ds_read_b128 v[194:197], v159 offset:21504
	ds_read_b128 v[202:205], v159 offset:22528
	ds_read_b128 v[206:209], v159 offset:23552
	global_load_lds_dwordx4 v[154:155], off
	s_add_i32 m0, s0, 0x2000
	s_add_u32 s22, s30, 0xb0000
	v_lshl_add_u64 v[210:211], s[30:31], 0, v[144:145]
	s_addc_u32 s23, s31, 0
	s_add_i32 s0, s33, s68
	global_load_lds_dwordx4 v[210:211], off
	v_lshl_add_u64 v[212:213], s[22:23], 0, v[192:193]
	s_mov_b32 m0, s0
	v_lshl_add_u64 v[214:215], s[66:67], 0, v[144:145]
	global_load_lds_dwordx4 v[212:213], off
	v_lshl_add_u64 v[212:213], s[22:23], 0, v[144:145]
	s_add_i32 m0, s0, 0x2000
	s_nop 0
	global_load_lds_dwordx4 v[212:213], off
	v_lshl_add_u64 v[212:213], s[66:67], 0, v[192:193]
	s_mov_b32 m0, s69
	s_nop 0
	global_load_lds_dwordx4 v[212:213], off
	s_mov_b32 m0, s70
	s_nop 0
	global_load_lds_dwordx4 v[214:215], off
	s_waitcnt vmcnt(8)
	s_waitcnt lgkmcnt(0)
	s_barrier
	s_setprio 1
	s_waitcnt lgkmcnt(0)
	v_mfma_f32_16x16x32_bf16 v[60:63], v[64:67], v[172:175], v[60:63]
	v_mfma_f32_16x16x32_bf16 v[56:59], v[72:75], v[172:175], v[56:59]
	v_mfma_f32_16x16x32_bf16 v[52:55], v[64:67], v[180:183], v[52:55]
	v_mfma_f32_16x16x32_bf16 v[48:51], v[72:75], v[180:183], v[48:51]
	v_mfma_f32_16x16x32_bf16 v[28:31], v[64:67], v[188:191], v[28:31]
	v_mfma_f32_16x16x32_bf16 v[24:27], v[72:75], v[188:191], v[24:27]
	v_mfma_f32_16x16x32_bf16 v[20:23], v[64:67], v[202:205], v[20:23]
	v_mfma_f32_16x16x32_bf16 v[8:11], v[72:75], v[202:205], v[8:11]
	v_mfma_f32_16x16x32_bf16 v[60:63], v[68:71], v[176:179], v[60:63]
	v_mfma_f32_16x16x32_bf16 v[56:59], v[76:79], v[176:179], v[56:59]
	v_mfma_f32_16x16x32_bf16 v[52:55], v[68:71], v[184:187], v[52:55]
	v_mfma_f32_16x16x32_bf16 v[48:51], v[76:79], v[184:187], v[48:51]
	v_mfma_f32_16x16x32_bf16 v[28:31], v[68:71], v[194:197], v[28:31]
	v_mfma_f32_16x16x32_bf16 v[24:27], v[76:79], v[194:197], v[24:27]
	v_mfma_f32_16x16x32_bf16 v[20:23], v[68:71], v[206:209], v[20:23]
	v_mfma_f32_16x16x32_bf16 v[8:11], v[76:79], v[206:209], v[8:11]
	v_mfma_f32_16x16x32_bf16 v[44:47], v[150:153], v[172:175], v[44:47]
	v_mfma_f32_16x16x32_bf16 v[40:43], v[164:167], v[172:175], v[40:43]
	v_mfma_f32_16x16x32_bf16 v[36:39], v[150:153], v[180:183], v[36:39]
	v_mfma_f32_16x16x32_bf16 v[32:35], v[164:167], v[180:183], v[32:35]
	v_mfma_f32_16x16x32_bf16 v[16:19], v[150:153], v[188:191], v[16:19]
	v_mfma_f32_16x16x32_bf16 v[12:15], v[164:167], v[188:191], v[12:15]
	v_mfma_f32_16x16x32_bf16 v[4:7], v[150:153], v[202:205], v[4:7]
	v_mfma_f32_16x16x32_bf16 v[0:3], v[164:167], v[202:205], v[0:3]
	v_mfma_f32_16x16x32_bf16 v[44:47], v[160:163], v[176:179], v[44:47]
	v_mfma_f32_16x16x32_bf16 v[40:43], v[168:171], v[176:179], v[40:43]
	v_mfma_f32_16x16x32_bf16 v[36:39], v[160:163], v[184:187], v[36:39]
	v_mfma_f32_16x16x32_bf16 v[32:35], v[168:171], v[184:187], v[32:35]
	v_mfma_f32_16x16x32_bf16 v[16:19], v[160:163], v[194:197], v[16:19]
	v_mfma_f32_16x16x32_bf16 v[12:15], v[168:171], v[194:197], v[12:15]
	v_mfma_f32_16x16x32_bf16 v[4:7], v[160:163], v[206:209], v[4:7]
	v_mfma_f32_16x16x32_bf16 v[0:3], v[168:171], v[206:209], v[0:3]
	s_setprio 0
	s_barrier
	s_add_i32 s0, 0, 0x18000
	s_add_i32 s33, 0, 0x1c000
	v_add_u32_e32 v76, s0, v157
	v_add_u32_e32 v168, s33, v157
	ds_read_b128 v[64:67], v76
	ds_read_b128 v[68:71], v76 offset:1024
	ds_read_b128 v[72:75], v76 offset:2048
	ds_read_b128 v[76:79], v76 offset:3072
	ds_read_b128 v[150:153], v168
	ds_read_b128 v[160:163], v168 offset:1024
	ds_read_b128 v[164:167], v168 offset:2048
	ds_read_b128 v[168:171], v168 offset:3072
	s_add_u32 s22, s66, 0xb0000
	s_addc_u32 s23, s67, 0
	s_mov_b32 m0, s71
	v_lshl_add_u64 v[216:217], s[22:23], 0, v[192:193]
	ds_read_b128 v[172:175], v159 offset:32768
	ds_read_b128 v[176:179], v159 offset:33792
	ds_read_b128 v[180:183], v159 offset:34816
	ds_read_b128 v[184:187], v159 offset:35840
	ds_read_b128 v[188:191], v159 offset:36864
	ds_read_b128 v[194:197], v159 offset:37888
	ds_read_b128 v[202:205], v159 offset:38912
	ds_read_b128 v[206:209], v159 offset:39936
	global_load_lds_dwordx4 v[216:217], off
	v_lshl_add_u64 v[216:217], s[22:23], 0, v[144:145]
	s_mov_b32 m0, s72
	s_nop 0
	global_load_lds_dwordx4 v[216:217], off
	s_waitcnt vmcnt(8)
	s_waitcnt lgkmcnt(0)
	s_barrier
	s_setprio 1
	s_waitcnt lgkmcnt(0)
	v_mfma_f32_16x16x32_bf16 v[140:143], v[64:67], v[172:175], v[140:143]
	v_mfma_f32_16x16x32_bf16 v[136:139], v[72:75], v[172:175], v[136:139]
	v_mfma_f32_16x16x32_bf16 v[132:135], v[64:67], v[180:183], v[132:135]
	v_mfma_f32_16x16x32_bf16 v[128:131], v[72:75], v[180:183], v[128:131]
	v_mfma_f32_16x16x32_bf16 v[108:111], v[64:67], v[188:191], v[108:111]
	v_mfma_f32_16x16x32_bf16 v[104:107], v[72:75], v[188:191], v[104:107]
	v_mfma_f32_16x16x32_bf16 v[100:103], v[64:67], v[202:205], v[100:103]
	v_mfma_f32_16x16x32_bf16 v[96:99], v[72:75], v[202:205], v[96:99]
	v_mfma_f32_16x16x32_bf16 v[140:143], v[68:71], v[176:179], v[140:143]
	v_mfma_f32_16x16x32_bf16 v[136:139], v[76:79], v[176:179], v[136:139]
	v_mfma_f32_16x16x32_bf16 v[132:135], v[68:71], v[184:187], v[132:135]
	v_mfma_f32_16x16x32_bf16 v[128:131], v[76:79], v[184:187], v[128:131]
	v_mfma_f32_16x16x32_bf16 v[108:111], v[68:71], v[194:197], v[108:111]
	v_mfma_f32_16x16x32_bf16 v[104:107], v[76:79], v[194:197], v[104:107]
	v_mfma_f32_16x16x32_bf16 v[100:103], v[68:71], v[206:209], v[100:103]
	v_mfma_f32_16x16x32_bf16 v[96:99], v[76:79], v[206:209], v[96:99]
	v_mfma_f32_16x16x32_bf16 v[124:127], v[150:153], v[172:175], v[124:127]
	v_mfma_f32_16x16x32_bf16 v[120:123], v[164:167], v[172:175], v[120:123]
	v_mfma_f32_16x16x32_bf16 v[116:119], v[150:153], v[180:183], v[116:119]
	v_mfma_f32_16x16x32_bf16 v[112:115], v[164:167], v[180:183], v[112:115]
	v_mfma_f32_16x16x32_bf16 v[92:95], v[150:153], v[188:191], v[92:95]
	v_mfma_f32_16x16x32_bf16 v[88:91], v[164:167], v[188:191], v[88:91]
	v_mfma_f32_16x16x32_bf16 v[84:87], v[150:153], v[202:205], v[84:87]
	v_mfma_f32_16x16x32_bf16 v[80:83], v[164:167], v[202:205], v[80:83]
	v_mfma_f32_16x16x32_bf16 v[124:127], v[160:163], v[176:179], v[124:127]
	v_mfma_f32_16x16x32_bf16 v[120:123], v[168:171], v[176:179], v[120:123]
	v_mfma_f32_16x16x32_bf16 v[116:119], v[160:163], v[184:187], v[116:119]
	v_mfma_f32_16x16x32_bf16 v[112:115], v[168:171], v[184:187], v[112:115]
	v_mfma_f32_16x16x32_bf16 v[92:95], v[160:163], v[194:197], v[92:95]
	v_mfma_f32_16x16x32_bf16 v[88:91], v[168:171], v[194:197], v[88:91]
	v_mfma_f32_16x16x32_bf16 v[84:87], v[160:163], v[206:209], v[84:87]
	v_mfma_f32_16x16x32_bf16 v[80:83], v[168:171], v[206:209], v[80:83]
	s_setprio 0
	s_barrier
	s_add_i32 s0, s0, s68
	v_lshl_add_u64 v[154:155], v[154:155], 0, s[40:41]
	s_mov_b32 m0, s0
	ds_read_b128 v[172:175], v159 offset:49152
	ds_read_b128 v[176:179], v159 offset:50176
	ds_read_b128 v[180:183], v159 offset:51200
	ds_read_b128 v[184:187], v159 offset:52224
	ds_read_b128 v[188:191], v159 offset:53248
	ds_read_b128 v[194:197], v159 offset:54272
	ds_read_b128 v[202:205], v159 offset:55296
	ds_read_b128 v[206:209], v159 offset:56320
	global_load_lds_dwordx4 v[154:155], off
	s_add_i32 m0, s0, 0x2000
	s_add_u32 s22, s30, 0xb0080
	v_lshl_add_u64 v[154:155], v[210:211], 0, s[40:41]
	s_addc_u32 s23, s31, 0
	s_add_i32 s0, s33, s68
	global_load_lds_dwordx4 v[154:155], off
	v_lshl_add_u64 v[154:155], s[22:23], 0, v[192:193]
	s_mov_b32 m0, s0
	s_nop 0
	global_load_lds_dwordx4 v[154:155], off
	v_lshl_add_u64 v[154:155], s[22:23], 0, v[144:145]
	s_add_i32 m0, s0, 0x2000
	s_nop 0
	global_load_lds_dwordx4 v[154:155], off
	v_lshl_add_u64 v[154:155], v[212:213], 0, s[40:41]
	s_mov_b32 m0, s76
	s_nop 0
	global_load_lds_dwordx4 v[154:155], off
	v_lshl_add_u64 v[154:155], v[214:215], 0, s[40:41]
	s_mov_b32 m0, s77
	s_nop 0
	global_load_lds_dwordx4 v[154:155], off
	s_waitcnt vmcnt(8)
	s_waitcnt lgkmcnt(0)
	s_barrier
	s_setprio 1
	s_waitcnt lgkmcnt(0)
	v_mfma_f32_16x16x32_bf16 v[60:63], v[64:67], v[172:175], v[60:63]
	v_mfma_f32_16x16x32_bf16 v[56:59], v[72:75], v[172:175], v[56:59]
	v_mfma_f32_16x16x32_bf16 v[52:55], v[64:67], v[180:183], v[52:55]
	v_mfma_f32_16x16x32_bf16 v[48:51], v[72:75], v[180:183], v[48:51]
	v_mfma_f32_16x16x32_bf16 v[28:31], v[64:67], v[188:191], v[28:31]
	v_mfma_f32_16x16x32_bf16 v[24:27], v[72:75], v[188:191], v[24:27]
	v_mfma_f32_16x16x32_bf16 v[20:23], v[64:67], v[202:205], v[20:23]
	v_mfma_f32_16x16x32_bf16 v[8:11], v[72:75], v[202:205], v[8:11]
	v_mfma_f32_16x16x32_bf16 v[60:63], v[68:71], v[176:179], v[60:63]
	v_mfma_f32_16x16x32_bf16 v[56:59], v[76:79], v[176:179], v[56:59]
	v_mfma_f32_16x16x32_bf16 v[52:55], v[68:71], v[184:187], v[52:55]
	v_mfma_f32_16x16x32_bf16 v[48:51], v[76:79], v[184:187], v[48:51]
	v_mfma_f32_16x16x32_bf16 v[28:31], v[68:71], v[194:197], v[28:31]
	v_mfma_f32_16x16x32_bf16 v[24:27], v[76:79], v[194:197], v[24:27]
	v_mfma_f32_16x16x32_bf16 v[20:23], v[68:71], v[206:209], v[20:23]
	v_mfma_f32_16x16x32_bf16 v[8:11], v[76:79], v[206:209], v[8:11]
	v_mfma_f32_16x16x32_bf16 v[44:47], v[150:153], v[172:175], v[44:47]
	v_mfma_f32_16x16x32_bf16 v[40:43], v[164:167], v[172:175], v[40:43]
	v_mfma_f32_16x16x32_bf16 v[36:39], v[150:153], v[180:183], v[36:39]
	v_mfma_f32_16x16x32_bf16 v[32:35], v[164:167], v[180:183], v[32:35]
	v_mfma_f32_16x16x32_bf16 v[16:19], v[150:153], v[188:191], v[16:19]
	v_mfma_f32_16x16x32_bf16 v[12:15], v[164:167], v[188:191], v[12:15]
	v_mfma_f32_16x16x32_bf16 v[4:7], v[150:153], v[202:205], v[4:7]
	v_mfma_f32_16x16x32_bf16 v[0:3], v[164:167], v[202:205], v[0:3]
	v_mfma_f32_16x16x32_bf16 v[44:47], v[160:163], v[176:179], v[44:47]
	v_mfma_f32_16x16x32_bf16 v[40:43], v[168:171], v[176:179], v[40:43]
	v_mfma_f32_16x16x32_bf16 v[36:39], v[160:163], v[184:187], v[36:39]
	v_mfma_f32_16x16x32_bf16 v[32:35], v[168:171], v[184:187], v[32:35]
	v_mfma_f32_16x16x32_bf16 v[16:19], v[160:163], v[194:197], v[16:19]
	v_mfma_f32_16x16x32_bf16 v[12:15], v[168:171], v[194:197], v[12:15]
	v_mfma_f32_16x16x32_bf16 v[4:7], v[160:163], v[206:209], v[4:7]
	v_mfma_f32_16x16x32_bf16 v[0:3], v[168:171], v[206:209], v[0:3]
	s_setprio 0
	s_barrier
	s_add_i32 s46, s46, 2
	s_add_u32 s1, s1, 0x100
	s_addc_u32 s38, s38, 0
	s_cmp_gt_u32 s46, 41
	s_mov_b64 s[22:23], s[26:27]
	s_cbranch_scc0 .LBB0_46
	s_and_b64 vcc, exec, s[14:15]
	s_cbranch_vccz .LBB0_49
	s_barrier

.LBB0_66:
	s_add_u32 s0, s68, 0xfffc0080
	s_addc_u32 s14, s69, -1
	s_add_i32 s15, 0, 0x10000
	s_cmp_eq_u32 s48, 12
	s_cselect_b32 s73, s23, s14
	s_cselect_b32 s72, s35, s0
	v_add_u32_e32 v138, s15, v141
	s_cselect_b32 s71, s1, s46
	s_cselect_b32 s70, s19, s38
	s_add_i32 s0, 0, 0x14000
	ds_read_b128 v[144:147], v138
	ds_read_b128 v[148:151], v138 offset:1024
	ds_read_b128 v[152:155], v138 offset:2048
	ds_read_b128 v[156:159], v138 offset:3072
	v_add_u32_e32 v138, s0, v141
	ds_read_b128 v[160:163], v138
	ds_read_b128 v[164:167], v138 offset:1024
	ds_read_b128 v[168:171], v138 offset:2048
	ds_read_b128 v[172:175], v138 offset:3072
	v_lshl_add_u64 v[138:139], s[68:69], 0, v[134:135]
	s_add_i32 m0, s67, 0xc000
	ds_read_b128 v[176:179], v143
	ds_read_b128 v[180:183], v143 offset:1024
	ds_read_b128 v[184:187], v143 offset:2048
	ds_read_b128 v[188:191], v143 offset:3072
	ds_read_b128 v[194:197], v143 offset:4096
	ds_read_b128 v[202:205], v143 offset:5120
	ds_read_b128 v[206:209], v143 offset:6144
	ds_read_b128 v[210:213], v143 offset:7168
	global_load_lds_dwordx4 v[138:139], off
	v_lshl_add_u64 v[138:139], s[68:69], 0, v[136:137]
	s_add_i32 m0, s67, 0xe000
	s_nop 0
	global_load_lds_dwordx4 v[138:139], off
	s_waitcnt vmcnt(8)
	s_waitcnt lgkmcnt(0)
	s_barrier
	s_setprio 1
	s_waitcnt lgkmcnt(0)
	v_mfma_f32_16x16x32_bf16 v[124:127], v[144:147], v[176:179], v[124:127]
	v_mfma_f32_16x16x32_bf16 v[120:123], v[152:155], v[176:179], v[120:123]
	v_mfma_f32_16x16x32_bf16 v[108:111], v[144:147], v[184:187], v[108:111]
	v_mfma_f32_16x16x32_bf16 v[104:107], v[152:155], v[184:187], v[104:107]
	v_mfma_f32_16x16x32_bf16 v[92:95], v[144:147], v[194:197], v[92:95]
	v_mfma_f32_16x16x32_bf16 v[88:91], v[152:155], v[194:197], v[88:91]
	v_mfma_f32_16x16x32_bf16 v[76:79], v[144:147], v[206:209], v[76:79]
	v_mfma_f32_16x16x32_bf16 v[72:75], v[152:155], v[206:209], v[72:75]
	v_mfma_f32_16x16x32_bf16 v[124:127], v[148:151], v[180:183], v[124:127]
	v_mfma_f32_16x16x32_bf16 v[120:123], v[156:159], v[180:183], v[120:123]
	v_mfma_f32_16x16x32_bf16 v[108:111], v[148:151], v[188:191], v[108:111]
	v_mfma_f32_16x16x32_bf16 v[104:107], v[156:159], v[188:191], v[104:107]
	v_mfma_f32_16x16x32_bf16 v[92:95], v[148:151], v[202:205], v[92:95]
	v_mfma_f32_16x16x32_bf16 v[88:91], v[156:159], v[202:205], v[88:91]
	v_mfma_f32_16x16x32_bf16 v[76:79], v[148:151], v[210:213], v[76:79]
	v_mfma_f32_16x16x32_bf16 v[72:75], v[156:159], v[210:213], v[72:75]
	v_mfma_f32_16x16x32_bf16 v[116:119], v[160:163], v[176:179], v[116:119]
	v_mfma_f32_16x16x32_bf16 v[112:115], v[168:171], v[176:179], v[112:115]
	v_mfma_f32_16x16x32_bf16 v[100:103], v[160:163], v[184:187], v[100:103]
	v_mfma_f32_16x16x32_bf16 v[96:99], v[168:171], v[184:187], v[96:99]
	v_mfma_f32_16x16x32_bf16 v[84:87], v[160:163], v[194:197], v[84:87]
	v_mfma_f32_16x16x32_bf16 v[80:83], v[168:171], v[194:197], v[80:83]
	v_mfma_f32_16x16x32_bf16 v[68:71], v[160:163], v[206:209], v[68:71]
	v_mfma_f32_16x16x32_bf16 v[64:67], v[168:171], v[206:209], v[64:67]
	v_mfma_f32_16x16x32_bf16 v[116:119], v[164:167], v[180:183], v[116:119]
	v_mfma_f32_16x16x32_bf16 v[112:115], v[172:175], v[180:183], v[112:115]
	v_mfma_f32_16x16x32_bf16 v[100:103], v[164:167], v[188:191], v[100:103]
	v_mfma_f32_16x16x32_bf16 v[96:99], v[172:175], v[188:191], v[96:99]
	v_mfma_f32_16x16x32_bf16 v[84:87], v[164:167], v[202:205], v[84:87]
	v_mfma_f32_16x16x32_bf16 v[80:83], v[172:175], v[202:205], v[80:83]
	v_mfma_f32_16x16x32_bf16 v[68:71], v[164:167], v[210:213], v[68:71]
	v_mfma_f32_16x16x32_bf16 v[64:67], v[172:175], v[210:213], v[64:67]
	s_setprio 0
	s_barrier
	s_add_i32 s14, s15, s74
	v_lshl_add_u64 v[138:139], s[70:71], 0, v[192:193]
	s_mov_b32 m0, s14
	ds_read_b128 v[176:179], v143 offset:16384
	ds_read_b128 v[180:183], v143 offset:17408
	ds_read_b128 v[184:187], v143 offset:18432
	ds_read_b128 v[188:191], v143 offset:19456
	ds_read_b128 v[194:197], v143 offset:20480
	ds_read_b128 v[202:205], v143 offset:21504
	ds_read_b128 v[206:209], v143 offset:22528
	ds_read_b128 v[210:213], v143 offset:23552
	global_load_lds_dwordx4 v[138:139], off
	s_add_i32 m0, s14, 0x2000
	s_add_u32 s14, s70, 0x40000
	v_lshl_add_u64 v[214:215], s[70:71], 0, v[128:129]
	s_addc_u32 s15, s71, 0
	s_add_i32 s0, s0, s74
	global_load_lds_dwordx4 v[214:215], off
	v_lshl_add_u64 v[216:217], s[14:15], 0, v[192:193]
	s_mov_b32 m0, s0
	v_lshl_add_u64 v[218:219], s[72:73], 0, v[130:131]
	global_load_lds_dwordx4 v[216:217], off
	v_lshl_add_u64 v[216:217], s[14:15], 0, v[128:129]
	s_add_i32 m0, s0, 0x2000
	s_nop 0
	global_load_lds_dwordx4 v[216:217], off
	v_lshl_add_u64 v[216:217], s[72:73], 0, v[132:133]
	s_mov_b32 m0, s67
	s_nop 0
	global_load_lds_dwordx4 v[216:217], off
	s_mov_b32 m0, s75
	s_nop 0
	global_load_lds_dwordx4 v[218:219], off
	s_waitcnt vmcnt(8)
	s_waitcnt lgkmcnt(0)
	s_barrier
	s_setprio 1
	s_waitcnt lgkmcnt(0)
	v_mfma_f32_16x16x32_bf16 v[60:63], v[144:147], v[176:179], v[60:63]
	v_mfma_f32_16x16x32_bf16 v[56:59], v[152:155], v[176:179], v[56:59]
	v_mfma_f32_16x16x32_bf16 v[44:47], v[144:147], v[184:187], v[44:47]
	v_mfma_f32_16x16x32_bf16 v[40:43], v[152:155], v[184:187], v[40:43]
	v_mfma_f32_16x16x32_bf16 v[28:31], v[144:147], v[194:197], v[28:31]
	v_mfma_f32_16x16x32_bf16 v[24:27], v[152:155], v[194:197], v[24:27]
	v_mfma_f32_16x16x32_bf16 v[12:15], v[144:147], v[206:209], v[12:15]
	v_mfma_f32_16x16x32_bf16 v[8:11], v[152:155], v[206:209], v[8:11]
	v_mfma_f32_16x16x32_bf16 v[60:63], v[148:151], v[180:183], v[60:63]
	v_mfma_f32_16x16x32_bf16 v[56:59], v[156:159], v[180:183], v[56:59]
	v_mfma_f32_16x16x32_bf16 v[44:47], v[148:151], v[188:191], v[44:47]
	v_mfma_f32_16x16x32_bf16 v[40:43], v[156:159], v[188:191], v[40:43]
	v_mfma_f32_16x16x32_bf16 v[28:31], v[148:151], v[202:205], v[28:31]
	v_mfma_f32_16x16x32_bf16 v[24:27], v[156:159], v[202:205], v[24:27]
	v_mfma_f32_16x16x32_bf16 v[12:15], v[148:151], v[210:213], v[12:15]
	v_mfma_f32_16x16x32_bf16 v[8:11], v[156:159], v[210:213], v[8:11]
	v_mfma_f32_16x16x32_bf16 v[52:55], v[160:163], v[176:179], v[52:55]
	v_mfma_f32_16x16x32_bf16 v[48:51], v[168:171], v[176:179], v[48:51]
	v_mfma_f32_16x16x32_bf16 v[36:39], v[160:163], v[184:187], v[36:39]
	v_mfma_f32_16x16x32_bf16 v[32:35], v[168:171], v[184:187], v[32:35]
	v_mfma_f32_16x16x32_bf16 v[20:23], v[160:163], v[194:197], v[20:23]
	v_mfma_f32_16x16x32_bf16 v[16:19], v[168:171], v[194:197], v[16:19]
	v_mfma_f32_16x16x32_bf16 v[4:7], v[160:163], v[206:209], v[4:7]
	v_mfma_f32_16x16x32_bf16 v[0:3], v[168:171], v[206:209], v[0:3]
	v_mfma_f32_16x16x32_bf16 v[52:55], v[164:167], v[180:183], v[52:55]
	v_mfma_f32_16x16x32_bf16 v[48:51], v[172:175], v[180:183], v[48:51]
	v_mfma_f32_16x16x32_bf16 v[36:39], v[164:167], v[188:191], v[36:39]
	v_mfma_f32_16x16x32_bf16 v[32:35], v[172:175], v[188:191], v[32:35]
	v_mfma_f32_16x16x32_bf16 v[20:23], v[164:167], v[202:205], v[20:23]
	v_mfma_f32_16x16x32_bf16 v[16:19], v[172:175], v[202:205], v[16:19]
	v_mfma_f32_16x16x32_bf16 v[4:7], v[164:167], v[210:213], v[4:7]
	v_mfma_f32_16x16x32_bf16 v[0:3], v[172:175], v[210:213], v[0:3]
	s_setprio 0
	s_barrier
	s_add_i32 s0, 0, 0x18000
	s_add_i32 s33, 0, 0x1c000
	v_add_u32_e32 v156, s0, v141
	v_add_u32_e32 v172, s33, v141
	ds_read_b128 v[144:147], v156
	ds_read_b128 v[148:151], v156 offset:1024
	ds_read_b128 v[152:155], v156 offset:2048
	ds_read_b128 v[156:159], v156 offset:3072
	ds_read_b128 v[160:163], v172
	ds_read_b128 v[164:167], v172 offset:1024
	ds_read_b128 v[168:171], v172 offset:2048
	ds_read_b128 v[172:175], v172 offset:3072
	s_add_u32 s14, s72, 0x40000
	s_addc_u32 s15, s73, 0
	s_mov_b32 m0, s76
	v_lshl_add_u64 v[226:227], s[14:15], 0, v[132:133]
	ds_read_b128 v[176:179], v143 offset:32768
	ds_read_b128 v[180:183], v143 offset:33792
	ds_read_b128 v[184:187], v143 offset:34816
	ds_read_b128 v[188:191], v143 offset:35840
	ds_read_b128 v[194:197], v143 offset:36864
	ds_read_b128 v[202:205], v143 offset:37888
	ds_read_b128 v[206:209], v143 offset:38912
	ds_read_b128 v[210:213], v143 offset:39936
	global_load_lds_dwordx4 v[226:227], off
	v_lshl_add_u64 v[226:227], s[14:15], 0, v[130:131]
	s_mov_b32 m0, s77
	s_nop 0
	global_load_lds_dwordx4 v[226:227], off
	s_waitcnt vmcnt(8)
	s_waitcnt lgkmcnt(0)
	s_barrier
	s_setprio 1
	s_waitcnt lgkmcnt(0)
	v_mfma_f32_16x16x32_bf16 v[124:127], v[144:147], v[176:179], v[124:127]
	v_mfma_f32_16x16x32_bf16 v[120:123], v[152:155], v[176:179], v[120:123]
	v_mfma_f32_16x16x32_bf16 v[108:111], v[144:147], v[184:187], v[108:111]
	v_mfma_f32_16x16x32_bf16 v[104:107], v[152:155], v[184:187], v[104:107]
	v_mfma_f32_16x16x32_bf16 v[92:95], v[144:147], v[194:197], v[92:95]
	v_mfma_f32_16x16x32_bf16 v[88:91], v[152:155], v[194:197], v[88:91]
	v_mfma_f32_16x16x32_bf16 v[76:79], v[144:147], v[206:209], v[76:79]
	v_mfma_f32_16x16x32_bf16 v[72:75], v[152:155], v[206:209], v[72:75]
	v_mfma_f32_16x16x32_bf16 v[124:127], v[148:151], v[180:183], v[124:127]
	v_mfma_f32_16x16x32_bf16 v[120:123], v[156:159], v[180:183], v[120:123]
	v_mfma_f32_16x16x32_bf16 v[108:111], v[148:151], v[188:191], v[108:111]
	v_mfma_f32_16x16x32_bf16 v[104:107], v[156:159], v[188:191], v[104:107]
	v_mfma_f32_16x16x32_bf16 v[92:95], v[148:151], v[202:205], v[92:95]
	v_mfma_f32_16x16x32_bf16 v[88:91], v[156:159], v[202:205], v[88:91]
	v_mfma_f32_16x16x32_bf16 v[76:79], v[148:151], v[210:213], v[76:79]
	v_mfma_f32_16x16x32_bf16 v[72:75], v[156:159], v[210:213], v[72:75]
	v_mfma_f32_16x16x32_bf16 v[116:119], v[160:163], v[176:179], v[116:119]
	v_mfma_f32_16x16x32_bf16 v[112:115], v[168:171], v[176:179], v[112:115]
	v_mfma_f32_16x16x32_bf16 v[100:103], v[160:163], v[184:187], v[100:103]
	v_mfma_f32_16x16x32_bf16 v[96:99], v[168:171], v[184:187], v[96:99]
	v_mfma_f32_16x16x32_bf16 v[84:87], v[160:163], v[194:197], v[84:87]
	v_mfma_f32_16x16x32_bf16 v[80:83], v[168:171], v[194:197], v[80:83]
	v_mfma_f32_16x16x32_bf16 v[68:71], v[160:163], v[206:209], v[68:71]
	v_mfma_f32_16x16x32_bf16 v[64:67], v[168:171], v[206:209], v[64:67]
	v_mfma_f32_16x16x32_bf16 v[116:119], v[164:167], v[180:183], v[116:119]
	v_mfma_f32_16x16x32_bf16 v[112:115], v[172:175], v[180:183], v[112:115]
	v_mfma_f32_16x16x32_bf16 v[100:103], v[164:167], v[188:191], v[100:103]
	v_mfma_f32_16x16x32_bf16 v[96:99], v[172:175], v[188:191], v[96:99]
	v_mfma_f32_16x16x32_bf16 v[84:87], v[164:167], v[202:205], v[84:87]
	v_mfma_f32_16x16x32_bf16 v[80:83], v[172:175], v[202:205], v[80:83]
	v_mfma_f32_16x16x32_bf16 v[68:71], v[164:167], v[210:213], v[68:71]
	v_mfma_f32_16x16x32_bf16 v[64:67], v[172:175], v[210:213], v[64:67]
	s_setprio 0
	s_barrier
	s_add_i32 s0, s0, s74
	v_lshl_add_u64 v[138:139], v[138:139], 0, s[40:41]
	s_mov_b32 m0, s0
	ds_read_b128 v[176:179], v143 offset:49152
	ds_read_b128 v[180:183], v143 offset:50176
	ds_read_b128 v[184:187], v143 offset:51200
	ds_read_b128 v[188:191], v143 offset:52224
	ds_read_b128 v[194:197], v143 offset:53248
	ds_read_b128 v[202:205], v143 offset:54272
	ds_read_b128 v[206:209], v143 offset:55296
	ds_read_b128 v[210:213], v143 offset:56320
	global_load_lds_dwordx4 v[138:139], off
	s_add_i32 m0, s0, 0x2000
	s_add_u32 s14, s70, 0x40080
	v_lshl_add_u64 v[138:139], v[214:215], 0, s[40:41]
	s_addc_u32 s15, s71, 0
	s_add_i32 s0, s33, s74
	global_load_lds_dwordx4 v[138:139], off
	v_lshl_add_u64 v[138:139], s[14:15], 0, v[192:193]
	s_mov_b32 m0, s0
	s_nop 0
	global_load_lds_dwordx4 v[138:139], off
	v_lshl_add_u64 v[138:139], s[14:15], 0, v[128:129]
	s_add_i32 m0, s0, 0x2000
	s_nop 0
	global_load_lds_dwordx4 v[138:139], off
	v_lshl_add_u64 v[138:139], v[216:217], 0, s[40:41]
	s_mov_b32 m0, s79
	s_nop 0
	global_load_lds_dwordx4 v[138:139], off
	v_lshl_add_u64 v[138:139], v[218:219], 0, s[40:41]
	s_mov_b32 m0, s80
	s_nop 0
	global_load_lds_dwordx4 v[138:139], off
	s_waitcnt vmcnt(8)
	s_waitcnt lgkmcnt(0)
	s_barrier
	s_setprio 1
	s_waitcnt lgkmcnt(0)
	v_mfma_f32_16x16x32_bf16 v[60:63], v[144:147], v[176:179], v[60:63]
	v_mfma_f32_16x16x32_bf16 v[56:59], v[152:155], v[176:179], v[56:59]
	v_mfma_f32_16x16x32_bf16 v[44:47], v[144:147], v[184:187], v[44:47]
	v_mfma_f32_16x16x32_bf16 v[40:43], v[152:155], v[184:187], v[40:43]
	v_mfma_f32_16x16x32_bf16 v[28:31], v[144:147], v[194:197], v[28:31]
	v_mfma_f32_16x16x32_bf16 v[24:27], v[152:155], v[194:197], v[24:27]
	v_mfma_f32_16x16x32_bf16 v[12:15], v[144:147], v[206:209], v[12:15]
	v_mfma_f32_16x16x32_bf16 v[8:11], v[152:155], v[206:209], v[8:11]
	v_mfma_f32_16x16x32_bf16 v[60:63], v[148:151], v[180:183], v[60:63]
	v_mfma_f32_16x16x32_bf16 v[56:59], v[156:159], v[180:183], v[56:59]
	v_mfma_f32_16x16x32_bf16 v[44:47], v[148:151], v[188:191], v[44:47]
	v_mfma_f32_16x16x32_bf16 v[40:43], v[156:159], v[188:191], v[40:43]
	v_mfma_f32_16x16x32_bf16 v[28:31], v[148:151], v[202:205], v[28:31]
	v_mfma_f32_16x16x32_bf16 v[24:27], v[156:159], v[202:205], v[24:27]
	v_mfma_f32_16x16x32_bf16 v[12:15], v[148:151], v[210:213], v[12:15]
	v_mfma_f32_16x16x32_bf16 v[8:11], v[156:159], v[210:213], v[8:11]
	v_mfma_f32_16x16x32_bf16 v[52:55], v[160:163], v[176:179], v[52:55]
	v_mfma_f32_16x16x32_bf16 v[48:51], v[168:171], v[176:179], v[48:51]
	v_mfma_f32_16x16x32_bf16 v[36:39], v[160:163], v[184:187], v[36:39]
	v_mfma_f32_16x16x32_bf16 v[32:35], v[168:171], v[184:187], v[32:35]
	v_mfma_f32_16x16x32_bf16 v[20:23], v[160:163], v[194:197], v[20:23]
	v_mfma_f32_16x16x32_bf16 v[16:19], v[168:171], v[194:197], v[16:19]
	v_mfma_f32_16x16x32_bf16 v[4:7], v[160:163], v[206:209], v[4:7]
	v_mfma_f32_16x16x32_bf16 v[0:3], v[168:171], v[206:209], v[0:3]
	v_mfma_f32_16x16x32_bf16 v[52:55], v[164:167], v[180:183], v[52:55]
	v_mfma_f32_16x16x32_bf16 v[48:51], v[172:175], v[180:183], v[48:51]
	v_mfma_f32_16x16x32_bf16 v[36:39], v[164:167], v[188:191], v[36:39]
	v_mfma_f32_16x16x32_bf16 v[32:35], v[172:175], v[188:191], v[32:35]
	v_mfma_f32_16x16x32_bf16 v[20:23], v[164:167], v[202:205], v[20:23]
	v_mfma_f32_16x16x32_bf16 v[16:19], v[172:175], v[202:205], v[16:19]
	v_mfma_f32_16x16x32_bf16 v[4:7], v[164:167], v[210:213], v[4:7]
	v_mfma_f32_16x16x32_bf16 v[0:3], v[172:175], v[210:213], v[0:3]
	s_setprio 0
	s_barrier
	s_add_i32 s48, s48, 2
	s_add_u32 s68, s68, 0x100
	s_addc_u32 s69, s69, 0
	s_add_u32 s38, s38, 0x100
	s_addc_u32 s46, s46, 0
	s_cmp_gt_u32 s48, 13
	s_cbranch_scc0 .LBB0_66
	s_and_b64 vcc, exec, s[16:17]
	s_cbranch_vccz .LBB0_69
	s_barrier

.LBB0_98:
	s_add_u32 s74, s72, 0x100
	s_addc_u32 s75, s73, 0
	s_add_i32 s0, 0, 0x10000
	s_cmp_eq_u32 s48, 12
	s_cselect_b32 s79, s31, s75
	s_cselect_b32 s78, s35, s74
	s_cselect_b32 s77, s1, s46
	s_cselect_b32 s76, s27, s38
	s_add_i32 s33, 0, 0x14000
	v_add_u32_e32 v76, s0, v157
	v_add_u32_e32 v154, s33, v157
	ds_read_b128 v[64:67], v76
	ds_read_b128 v[68:71], v76 offset:1024
	ds_read_b128 v[72:75], v76 offset:2048
	ds_read_b128 v[76:79], v76 offset:3072
	ds_read_b128 v[150:153], v154
	ds_read_b128 v[160:163], v154 offset:1024
	ds_read_b128 v[164:167], v154 offset:2048
	ds_read_b128 v[168:171], v154 offset:3072
	v_lshl_add_u64 v[154:155], s[72:73], 0, v[146:147]
	s_add_i32 m0, s81, 0xc000
	ds_read_b128 v[172:175], v159
	ds_read_b128 v[176:179], v159 offset:1024
	ds_read_b128 v[180:183], v159 offset:2048
	ds_read_b128 v[184:187], v159 offset:3072
	ds_read_b128 v[188:191], v159 offset:4096
	ds_read_b128 v[194:197], v159 offset:5120
	ds_read_b128 v[202:205], v159 offset:6144
	ds_read_b128 v[206:209], v159 offset:7168
	global_load_lds_dwordx4 v[154:155], off
	v_lshl_add_u64 v[154:155], s[72:73], 0, v[148:149]
	s_add_i32 m0, s81, 0xe000
	s_nop 0
	global_load_lds_dwordx4 v[154:155], off
	s_waitcnt vmcnt(8)
	s_waitcnt lgkmcnt(0)
	s_barrier
	s_setprio 1
	s_waitcnt lgkmcnt(0)
	v_mfma_f32_16x16x32_bf16 v[140:143], v[64:67], v[172:175], v[140:143]
	v_mfma_f32_16x16x32_bf16 v[136:139], v[72:75], v[172:175], v[136:139]
	v_mfma_f32_16x16x32_bf16 v[132:135], v[64:67], v[180:183], v[132:135]
	v_mfma_f32_16x16x32_bf16 v[128:131], v[72:75], v[180:183], v[128:131]
	v_mfma_f32_16x16x32_bf16 v[108:111], v[64:67], v[188:191], v[108:111]
	v_mfma_f32_16x16x32_bf16 v[104:107], v[72:75], v[188:191], v[104:107]
	v_mfma_f32_16x16x32_bf16 v[100:103], v[64:67], v[202:205], v[100:103]
	v_mfma_f32_16x16x32_bf16 v[96:99], v[72:75], v[202:205], v[96:99]
	v_mfma_f32_16x16x32_bf16 v[140:143], v[68:71], v[176:179], v[140:143]
	v_mfma_f32_16x16x32_bf16 v[136:139], v[76:79], v[176:179], v[136:139]
	v_mfma_f32_16x16x32_bf16 v[132:135], v[68:71], v[184:187], v[132:135]
	v_mfma_f32_16x16x32_bf16 v[128:131], v[76:79], v[184:187], v[128:131]
	v_mfma_f32_16x16x32_bf16 v[108:111], v[68:71], v[194:197], v[108:111]
	v_mfma_f32_16x16x32_bf16 v[104:107], v[76:79], v[194:197], v[104:107]
	v_mfma_f32_16x16x32_bf16 v[100:103], v[68:71], v[206:209], v[100:103]
	v_mfma_f32_16x16x32_bf16 v[96:99], v[76:79], v[206:209], v[96:99]
	v_mfma_f32_16x16x32_bf16 v[124:127], v[150:153], v[172:175], v[124:127]
	v_mfma_f32_16x16x32_bf16 v[120:123], v[164:167], v[172:175], v[120:123]
	v_mfma_f32_16x16x32_bf16 v[116:119], v[150:153], v[180:183], v[116:119]
	v_mfma_f32_16x16x32_bf16 v[112:115], v[164:167], v[180:183], v[112:115]
	v_mfma_f32_16x16x32_bf16 v[92:95], v[150:153], v[188:191], v[92:95]
	v_mfma_f32_16x16x32_bf16 v[88:91], v[164:167], v[188:191], v[88:91]
	v_mfma_f32_16x16x32_bf16 v[84:87], v[150:153], v[202:205], v[84:87]
	v_mfma_f32_16x16x32_bf16 v[80:83], v[164:167], v[202:205], v[80:83]
	v_mfma_f32_16x16x32_bf16 v[124:127], v[160:163], v[176:179], v[124:127]
	v_mfma_f32_16x16x32_bf16 v[120:123], v[168:171], v[176:179], v[120:123]
	v_mfma_f32_16x16x32_bf16 v[116:119], v[160:163], v[184:187], v[116:119]
	v_mfma_f32_16x16x32_bf16 v[112:115], v[168:171], v[184:187], v[112:115]
	v_mfma_f32_16x16x32_bf16 v[92:95], v[160:163], v[194:197], v[92:95]
	v_mfma_f32_16x16x32_bf16 v[88:91], v[168:171], v[194:197], v[88:91]
	v_mfma_f32_16x16x32_bf16 v[84:87], v[160:163], v[206:209], v[84:87]
	v_mfma_f32_16x16x32_bf16 v[80:83], v[168:171], v[206:209], v[80:83]
	s_setprio 0
	s_barrier
	s_add_i32 s0, s0, s29
	v_lshl_add_u64 v[154:155], s[76:77], 0, v[192:193]
	s_mov_b32 m0, s0
	ds_read_b128 v[172:175], v159 offset:16384
	ds_read_b128 v[176:179], v159 offset:17408
	ds_read_b128 v[180:183], v159 offset:18432
	ds_read_b128 v[184:187], v159 offset:19456
	ds_read_b128 v[188:191], v159 offset:20480
	ds_read_b128 v[194:197], v159 offset:21504
	ds_read_b128 v[202:205], v159 offset:22528
	ds_read_b128 v[206:209], v159 offset:23552
	global_load_lds_dwordx4 v[154:155], off
	s_add_i32 m0, s0, 0x2000
	s_add_u32 s14, s76, 0x40000
	v_lshl_add_u64 v[210:211], s[76:77], 0, v[144:145]
	s_addc_u32 s15, s77, 0
	s_add_i32 s0, s33, s29
	global_load_lds_dwordx4 v[210:211], off
	v_lshl_add_u64 v[212:213], s[14:15], 0, v[192:193]
	s_mov_b32 m0, s0
	v_lshl_add_u64 v[214:215], s[78:79], 0, v[144:145]
	global_load_lds_dwordx4 v[212:213], off
	v_lshl_add_u64 v[212:213], s[14:15], 0, v[144:145]
	s_add_i32 m0, s0, 0x2000
	s_nop 0
	global_load_lds_dwordx4 v[212:213], off
	v_lshl_add_u64 v[212:213], s[78:79], 0, v[192:193]
	s_mov_b32 m0, s81
	s_nop 0
	global_load_lds_dwordx4 v[212:213], off
	s_mov_b32 m0, s82
	s_nop 0
	global_load_lds_dwordx4 v[214:215], off
	s_waitcnt vmcnt(8)
	s_waitcnt lgkmcnt(0)
	s_barrier
	s_setprio 1
	s_waitcnt lgkmcnt(0)
	v_mfma_f32_16x16x32_bf16 v[60:63], v[64:67], v[172:175], v[60:63]
	v_mfma_f32_16x16x32_bf16 v[56:59], v[72:75], v[172:175], v[56:59]
	v_mfma_f32_16x16x32_bf16 v[52:55], v[64:67], v[180:183], v[52:55]
	v_mfma_f32_16x16x32_bf16 v[48:51], v[72:75], v[180:183], v[48:51]
	v_mfma_f32_16x16x32_bf16 v[28:31], v[64:67], v[188:191], v[28:31]
	v_mfma_f32_16x16x32_bf16 v[24:27], v[72:75], v[188:191], v[24:27]
	v_mfma_f32_16x16x32_bf16 v[20:23], v[64:67], v[202:205], v[20:23]
	v_mfma_f32_16x16x32_bf16 v[8:11], v[72:75], v[202:205], v[8:11]
	v_mfma_f32_16x16x32_bf16 v[60:63], v[68:71], v[176:179], v[60:63]
	v_mfma_f32_16x16x32_bf16 v[56:59], v[76:79], v[176:179], v[56:59]
	v_mfma_f32_16x16x32_bf16 v[52:55], v[68:71], v[184:187], v[52:55]
	v_mfma_f32_16x16x32_bf16 v[48:51], v[76:79], v[184:187], v[48:51]
	v_mfma_f32_16x16x32_bf16 v[28:31], v[68:71], v[194:197], v[28:31]
	v_mfma_f32_16x16x32_bf16 v[24:27], v[76:79], v[194:197], v[24:27]
	v_mfma_f32_16x16x32_bf16 v[20:23], v[68:71], v[206:209], v[20:23]
	v_mfma_f32_16x16x32_bf16 v[8:11], v[76:79], v[206:209], v[8:11]
	v_mfma_f32_16x16x32_bf16 v[44:47], v[150:153], v[172:175], v[44:47]
	v_mfma_f32_16x16x32_bf16 v[40:43], v[164:167], v[172:175], v[40:43]
	v_mfma_f32_16x16x32_bf16 v[36:39], v[150:153], v[180:183], v[36:39]
	v_mfma_f32_16x16x32_bf16 v[32:35], v[164:167], v[180:183], v[32:35]
	v_mfma_f32_16x16x32_bf16 v[16:19], v[150:153], v[188:191], v[16:19]
	v_mfma_f32_16x16x32_bf16 v[12:15], v[164:167], v[188:191], v[12:15]
	v_mfma_f32_16x16x32_bf16 v[4:7], v[150:153], v[202:205], v[4:7]
	v_mfma_f32_16x16x32_bf16 v[0:3], v[164:167], v[202:205], v[0:3]
	v_mfma_f32_16x16x32_bf16 v[44:47], v[160:163], v[176:179], v[44:47]
	v_mfma_f32_16x16x32_bf16 v[40:43], v[168:171], v[176:179], v[40:43]
	v_mfma_f32_16x16x32_bf16 v[36:39], v[160:163], v[184:187], v[36:39]
	v_mfma_f32_16x16x32_bf16 v[32:35], v[168:171], v[184:187], v[32:35]
	v_mfma_f32_16x16x32_bf16 v[16:19], v[160:163], v[194:197], v[16:19]
	v_mfma_f32_16x16x32_bf16 v[12:15], v[168:171], v[194:197], v[12:15]
	v_mfma_f32_16x16x32_bf16 v[4:7], v[160:163], v[206:209], v[4:7]
	v_mfma_f32_16x16x32_bf16 v[0:3], v[168:171], v[206:209], v[0:3]
	s_setprio 0
	s_barrier
	s_add_i32 s0, 0, 0x18000
	s_add_i32 s33, 0, 0x1c000
	v_add_u32_e32 v76, s0, v157
	v_add_u32_e32 v168, s33, v157
	ds_read_b128 v[64:67], v76
	ds_read_b128 v[68:71], v76 offset:1024
	ds_read_b128 v[72:75], v76 offset:2048
	ds_read_b128 v[76:79], v76 offset:3072
	ds_read_b128 v[150:153], v168
	ds_read_b128 v[160:163], v168 offset:1024
	ds_read_b128 v[164:167], v168 offset:2048
	ds_read_b128 v[168:171], v168 offset:3072
	s_add_u32 s14, s78, 0x40000
	s_addc_u32 s15, s79, 0
	s_mov_b32 m0, s83
	v_lshl_add_u64 v[216:217], s[14:15], 0, v[192:193]
	ds_read_b128 v[172:175], v159 offset:32768
	ds_read_b128 v[176:179], v159 offset:33792
	ds_read_b128 v[180:183], v159 offset:34816
	ds_read_b128 v[184:187], v159 offset:35840
	ds_read_b128 v[188:191], v159 offset:36864
	ds_read_b128 v[194:197], v159 offset:37888
	ds_read_b128 v[202:205], v159 offset:38912
	ds_read_b128 v[206:209], v159 offset:39936
	global_load_lds_dwordx4 v[216:217], off
	v_lshl_add_u64 v[216:217], s[14:15], 0, v[144:145]
	s_mov_b32 m0, s84
	s_nop 0
	global_load_lds_dwordx4 v[216:217], off
	s_waitcnt vmcnt(8)
	s_waitcnt lgkmcnt(0)
	s_barrier
	s_setprio 1
	s_waitcnt lgkmcnt(0)
	v_mfma_f32_16x16x32_bf16 v[140:143], v[64:67], v[172:175], v[140:143]
	v_mfma_f32_16x16x32_bf16 v[136:139], v[72:75], v[172:175], v[136:139]
	v_mfma_f32_16x16x32_bf16 v[132:135], v[64:67], v[180:183], v[132:135]
	v_mfma_f32_16x16x32_bf16 v[128:131], v[72:75], v[180:183], v[128:131]
	v_mfma_f32_16x16x32_bf16 v[108:111], v[64:67], v[188:191], v[108:111]
	v_mfma_f32_16x16x32_bf16 v[104:107], v[72:75], v[188:191], v[104:107]
	v_mfma_f32_16x16x32_bf16 v[100:103], v[64:67], v[202:205], v[100:103]
	v_mfma_f32_16x16x32_bf16 v[96:99], v[72:75], v[202:205], v[96:99]
	v_mfma_f32_16x16x32_bf16 v[140:143], v[68:71], v[176:179], v[140:143]
	v_mfma_f32_16x16x32_bf16 v[136:139], v[76:79], v[176:179], v[136:139]
	v_mfma_f32_16x16x32_bf16 v[132:135], v[68:71], v[184:187], v[132:135]
	v_mfma_f32_16x16x32_bf16 v[128:131], v[76:79], v[184:187], v[128:131]
	v_mfma_f32_16x16x32_bf16 v[108:111], v[68:71], v[194:197], v[108:111]
	v_mfma_f32_16x16x32_bf16 v[104:107], v[76:79], v[194:197], v[104:107]
	v_mfma_f32_16x16x32_bf16 v[100:103], v[68:71], v[206:209], v[100:103]
	v_mfma_f32_16x16x32_bf16 v[96:99], v[76:79], v[206:209], v[96:99]
	v_mfma_f32_16x16x32_bf16 v[124:127], v[150:153], v[172:175], v[124:127]
	v_mfma_f32_16x16x32_bf16 v[120:123], v[164:167], v[172:175], v[120:123]
	v_mfma_f32_16x16x32_bf16 v[116:119], v[150:153], v[180:183], v[116:119]
	v_mfma_f32_16x16x32_bf16 v[112:115], v[164:167], v[180:183], v[112:115]
	v_mfma_f32_16x16x32_bf16 v[92:95], v[150:153], v[188:191], v[92:95]
	v_mfma_f32_16x16x32_bf16 v[88:91], v[164:167], v[188:191], v[88:91]
	v_mfma_f32_16x16x32_bf16 v[84:87], v[150:153], v[202:205], v[84:87]
	v_mfma_f32_16x16x32_bf16 v[80:83], v[164:167], v[202:205], v[80:83]
	v_mfma_f32_16x16x32_bf16 v[124:127], v[160:163], v[176:179], v[124:127]
	v_mfma_f32_16x16x32_bf16 v[120:123], v[168:171], v[176:179], v[120:123]
	v_mfma_f32_16x16x32_bf16 v[116:119], v[160:163], v[184:187], v[116:119]
	v_mfma_f32_16x16x32_bf16 v[112:115], v[168:171], v[184:187], v[112:115]
	v_mfma_f32_16x16x32_bf16 v[92:95], v[160:163], v[194:197], v[92:95]
	v_mfma_f32_16x16x32_bf16 v[88:91], v[168:171], v[194:197], v[88:91]
	v_mfma_f32_16x16x32_bf16 v[84:87], v[160:163], v[206:209], v[84:87]
	v_mfma_f32_16x16x32_bf16 v[80:83], v[168:171], v[206:209], v[80:83]
	s_setprio 0
	s_barrier
	s_add_i32 s0, s0, s29
	v_lshl_add_u64 v[154:155], v[154:155], 0, s[40:41]
	s_mov_b32 m0, s0
	ds_read_b128 v[172:175], v159 offset:49152
	ds_read_b128 v[176:179], v159 offset:50176
	ds_read_b128 v[180:183], v159 offset:51200
	ds_read_b128 v[184:187], v159 offset:52224
	ds_read_b128 v[188:191], v159 offset:53248
	ds_read_b128 v[194:197], v159 offset:54272
	ds_read_b128 v[202:205], v159 offset:55296
	ds_read_b128 v[206:209], v159 offset:56320
	global_load_lds_dwordx4 v[154:155], off
	s_add_i32 m0, s0, 0x2000
	s_add_u32 s14, s76, 0x40080
	v_lshl_add_u64 v[154:155], v[210:211], 0, s[40:41]
	s_addc_u32 s15, s77, 0
	s_add_i32 s0, s33, s29
	global_load_lds_dwordx4 v[154:155], off
	v_lshl_add_u64 v[154:155], s[14:15], 0, v[192:193]
	s_mov_b32 m0, s0
	s_nop 0
	global_load_lds_dwordx4 v[154:155], off
	v_lshl_add_u64 v[154:155], s[14:15], 0, v[144:145]
	s_add_i32 m0, s0, 0x2000
	s_nop 0
	global_load_lds_dwordx4 v[154:155], off
	v_lshl_add_u64 v[154:155], v[212:213], 0, s[40:41]
	s_mov_b32 m0, s88
	s_nop 0
	global_load_lds_dwordx4 v[154:155], off
	v_lshl_add_u64 v[154:155], v[214:215], 0, s[40:41]
	s_mov_b32 m0, s89
	s_nop 0
	global_load_lds_dwordx4 v[154:155], off
	s_waitcnt vmcnt(8)
	s_waitcnt lgkmcnt(0)
	s_barrier
	s_setprio 1
	s_waitcnt lgkmcnt(0)
	v_mfma_f32_16x16x32_bf16 v[60:63], v[64:67], v[172:175], v[60:63]
	v_mfma_f32_16x16x32_bf16 v[56:59], v[72:75], v[172:175], v[56:59]
	v_mfma_f32_16x16x32_bf16 v[52:55], v[64:67], v[180:183], v[52:55]
	v_mfma_f32_16x16x32_bf16 v[48:51], v[72:75], v[180:183], v[48:51]
	v_mfma_f32_16x16x32_bf16 v[28:31], v[64:67], v[188:191], v[28:31]
	v_mfma_f32_16x16x32_bf16 v[24:27], v[72:75], v[188:191], v[24:27]
	v_mfma_f32_16x16x32_bf16 v[20:23], v[64:67], v[202:205], v[20:23]
	v_mfma_f32_16x16x32_bf16 v[8:11], v[72:75], v[202:205], v[8:11]
	v_mfma_f32_16x16x32_bf16 v[60:63], v[68:71], v[176:179], v[60:63]
	v_mfma_f32_16x16x32_bf16 v[56:59], v[76:79], v[176:179], v[56:59]
	v_mfma_f32_16x16x32_bf16 v[52:55], v[68:71], v[184:187], v[52:55]
	v_mfma_f32_16x16x32_bf16 v[48:51], v[76:79], v[184:187], v[48:51]
	v_mfma_f32_16x16x32_bf16 v[28:31], v[68:71], v[194:197], v[28:31]
	v_mfma_f32_16x16x32_bf16 v[24:27], v[76:79], v[194:197], v[24:27]
	v_mfma_f32_16x16x32_bf16 v[20:23], v[68:71], v[206:209], v[20:23]
	v_mfma_f32_16x16x32_bf16 v[8:11], v[76:79], v[206:209], v[8:11]
	v_mfma_f32_16x16x32_bf16 v[44:47], v[150:153], v[172:175], v[44:47]
	v_mfma_f32_16x16x32_bf16 v[40:43], v[164:167], v[172:175], v[40:43]
	v_mfma_f32_16x16x32_bf16 v[36:39], v[150:153], v[180:183], v[36:39]
	v_mfma_f32_16x16x32_bf16 v[32:35], v[164:167], v[180:183], v[32:35]
	v_mfma_f32_16x16x32_bf16 v[16:19], v[150:153], v[188:191], v[16:19]
	v_mfma_f32_16x16x32_bf16 v[12:15], v[164:167], v[188:191], v[12:15]
	v_mfma_f32_16x16x32_bf16 v[4:7], v[150:153], v[202:205], v[4:7]
	v_mfma_f32_16x16x32_bf16 v[0:3], v[164:167], v[202:205], v[0:3]
	v_mfma_f32_16x16x32_bf16 v[44:47], v[160:163], v[176:179], v[44:47]
	v_mfma_f32_16x16x32_bf16 v[40:43], v[168:171], v[176:179], v[40:43]
	v_mfma_f32_16x16x32_bf16 v[36:39], v[160:163], v[184:187], v[36:39]
	v_mfma_f32_16x16x32_bf16 v[32:35], v[168:171], v[184:187], v[32:35]
	v_mfma_f32_16x16x32_bf16 v[16:19], v[160:163], v[194:197], v[16:19]
	v_mfma_f32_16x16x32_bf16 v[12:15], v[168:171], v[194:197], v[12:15]
	v_mfma_f32_16x16x32_bf16 v[4:7], v[160:163], v[206:209], v[4:7]
	v_mfma_f32_16x16x32_bf16 v[0:3], v[168:171], v[206:209], v[0:3]
	s_setprio 0
	s_barrier
	s_add_i32 s48, s48, 2
	s_add_u32 s38, s38, 0x100
	s_addc_u32 s46, s46, 0
	s_cmp_gt_u32 s48, 13
	s_mov_b64 s[72:73], s[74:75]
	s_cbranch_scc0 .LBB0_98
	s_and_b64 vcc, exec, s[10:11]
	s_cbranch_vccz .LBB0_101
	s_barrier

.LBB0_116:
	s_add_u32 s0, s70, 0xfffe0080
	s_addc_u32 s14, s71, -1
	s_add_i32 s15, 0, 0x10000
	s_cmp_eq_u32 s34, 4
	s_cselect_b32 s75, s2, s14
	s_cselect_b32 s74, s12, s0
	s_cselect_b32 s73, s1, s19
	s_cselect_b32 s72, s13, s17
	s_add_i32 s0, 0, 0x14000
	v_add_u32_e32 v136, s15, v185
	v_add_u32_e32 v156, s0, v185
	ds_read_b128 v[108:111], v136
	ds_read_b128 v[120:123], v136 offset:1024
	ds_read_b128 v[128:131], v136 offset:2048
	ds_read_b128 v[136:139], v136 offset:3072
	ds_read_b128 v[144:147], v156
	ds_read_b128 v[148:151], v156 offset:1024
	ds_read_b128 v[152:155], v156 offset:2048
	ds_read_b128 v[156:159], v156 offset:3072
	v_lshl_add_u64 v[214:215], s[70:71], 0, v[168:169]
	s_add_i32 m0, s81, 0xc000
	ds_read_b128 v[172:175], v187
	ds_read_b128 v[176:179], v187 offset:1024
	ds_read_b128 v[180:183], v187 offset:2048
	ds_read_b128 v[188:191], v187 offset:3072
	ds_read_b128 v[194:197], v187 offset:4096
	ds_read_b128 v[202:205], v187 offset:5120
	ds_read_b128 v[206:209], v187 offset:6144
	ds_read_b128 v[210:213], v187 offset:7168
	global_load_lds_dwordx4 v[214:215], off
	v_lshl_add_u64 v[214:215], s[70:71], 0, v[170:171]
	s_add_i32 m0, s81, 0xe000
	s_nop 0
	global_load_lds_dwordx4 v[214:215], off
	s_waitcnt vmcnt(8)
	s_waitcnt lgkmcnt(0)
	s_barrier
	s_setprio 1
	s_waitcnt lgkmcnt(0)
	v_mfma_f32_16x16x32_bf16 v[140:143], v[108:111], v[172:175], v[140:143]
	v_mfma_f32_16x16x32_bf16 v[132:135], v[128:131], v[172:175], v[132:135]
	v_mfma_f32_16x16x32_bf16 v[112:115], v[108:111], v[180:183], v[112:115]
	v_mfma_f32_16x16x32_bf16 v[104:107], v[128:131], v[180:183], v[104:107]
	v_mfma_f32_16x16x32_bf16 v[92:95], v[108:111], v[194:197], v[92:95]
	v_mfma_f32_16x16x32_bf16 v[88:91], v[128:131], v[194:197], v[88:91]
	v_mfma_f32_16x16x32_bf16 v[76:79], v[108:111], v[206:209], v[76:79]
	v_mfma_f32_16x16x32_bf16 v[72:75], v[128:131], v[206:209], v[72:75]
	v_mfma_f32_16x16x32_bf16 v[140:143], v[120:123], v[176:179], v[140:143]
	v_mfma_f32_16x16x32_bf16 v[132:135], v[136:139], v[176:179], v[132:135]
	v_mfma_f32_16x16x32_bf16 v[112:115], v[120:123], v[188:191], v[112:115]
	v_mfma_f32_16x16x32_bf16 v[104:107], v[136:139], v[188:191], v[104:107]
	v_mfma_f32_16x16x32_bf16 v[92:95], v[120:123], v[202:205], v[92:95]
	v_mfma_f32_16x16x32_bf16 v[88:91], v[136:139], v[202:205], v[88:91]
	v_mfma_f32_16x16x32_bf16 v[76:79], v[120:123], v[210:213], v[76:79]
	v_mfma_f32_16x16x32_bf16 v[72:75], v[136:139], v[210:213], v[72:75]
	v_mfma_f32_16x16x32_bf16 v[124:127], v[144:147], v[172:175], v[124:127]
	v_mfma_f32_16x16x32_bf16 v[116:119], v[152:155], v[172:175], v[116:119]
	v_mfma_f32_16x16x32_bf16 v[100:103], v[144:147], v[180:183], v[100:103]
	v_mfma_f32_16x16x32_bf16 v[96:99], v[152:155], v[180:183], v[96:99]
	v_mfma_f32_16x16x32_bf16 v[84:87], v[144:147], v[194:197], v[84:87]
	v_mfma_f32_16x16x32_bf16 v[80:83], v[152:155], v[194:197], v[80:83]
	v_mfma_f32_16x16x32_bf16 v[68:71], v[144:147], v[206:209], v[68:71]
	v_mfma_f32_16x16x32_bf16 v[64:67], v[152:155], v[206:209], v[64:67]
	v_mfma_f32_16x16x32_bf16 v[124:127], v[148:151], v[176:179], v[124:127]
	v_mfma_f32_16x16x32_bf16 v[116:119], v[156:159], v[176:179], v[116:119]
	v_mfma_f32_16x16x32_bf16 v[100:103], v[148:151], v[188:191], v[100:103]
	v_mfma_f32_16x16x32_bf16 v[96:99], v[156:159], v[188:191], v[96:99]
	v_mfma_f32_16x16x32_bf16 v[84:87], v[148:151], v[202:205], v[84:87]
	v_mfma_f32_16x16x32_bf16 v[80:83], v[156:159], v[202:205], v[80:83]
	v_mfma_f32_16x16x32_bf16 v[68:71], v[148:151], v[210:213], v[68:71]
	v_mfma_f32_16x16x32_bf16 v[64:67], v[156:159], v[210:213], v[64:67]
	s_setprio 0
	s_barrier
	s_add_i32 s14, s15, s80
	v_lshl_add_u64 v[214:215], s[72:73], 0, v[164:165]
	s_mov_b32 m0, s14
	ds_read_b128 v[172:175], v187 offset:16384
	ds_read_b128 v[176:179], v187 offset:17408
	ds_read_b128 v[180:183], v187 offset:18432
	ds_read_b128 v[188:191], v187 offset:19456
	ds_read_b128 v[194:197], v187 offset:20480
	ds_read_b128 v[202:205], v187 offset:21504
	ds_read_b128 v[206:209], v187 offset:22528
	ds_read_b128 v[210:213], v187 offset:23552
	global_load_lds_dwordx4 v[214:215], off
	s_add_i32 m0, s14, 0x2000
	s_add_u32 s14, s72, 0x20000
	v_lshl_add_u64 v[216:217], s[72:73], 0, v[160:161]
	s_addc_u32 s15, s73, 0
	s_add_i32 s0, s0, s80
	global_load_lds_dwordx4 v[216:217], off
	v_lshl_add_u64 v[218:219], s[14:15], 0, v[164:165]
	s_mov_b32 m0, s0
	v_lshl_add_u64 v[226:227], s[74:75], 0, v[162:163]
	global_load_lds_dwordx4 v[218:219], off
	v_lshl_add_u64 v[218:219], s[14:15], 0, v[160:161]
	s_add_i32 m0, s0, 0x2000
	s_nop 0
	global_load_lds_dwordx4 v[218:219], off
	v_lshl_add_u64 v[218:219], s[74:75], 0, v[166:167]
	s_mov_b32 m0, s81
	s_nop 0
	global_load_lds_dwordx4 v[218:219], off
	s_mov_b32 m0, s82
	s_nop 0
	global_load_lds_dwordx4 v[226:227], off
	s_waitcnt vmcnt(8)
	s_waitcnt lgkmcnt(0)
	s_barrier
	s_setprio 1
	s_waitcnt lgkmcnt(0)
	v_mfma_f32_16x16x32_bf16 v[60:63], v[108:111], v[172:175], v[60:63]
	v_mfma_f32_16x16x32_bf16 v[56:59], v[128:131], v[172:175], v[56:59]
	v_mfma_f32_16x16x32_bf16 v[44:47], v[108:111], v[180:183], v[44:47]
	v_mfma_f32_16x16x32_bf16 v[40:43], v[128:131], v[180:183], v[40:43]
	v_mfma_f32_16x16x32_bf16 v[28:31], v[108:111], v[194:197], v[28:31]
	v_mfma_f32_16x16x32_bf16 v[24:27], v[128:131], v[194:197], v[24:27]
	v_mfma_f32_16x16x32_bf16 v[12:15], v[108:111], v[206:209], v[12:15]
	v_mfma_f32_16x16x32_bf16 v[8:11], v[128:131], v[206:209], v[8:11]
	v_mfma_f32_16x16x32_bf16 v[60:63], v[120:123], v[176:179], v[60:63]
	v_mfma_f32_16x16x32_bf16 v[56:59], v[136:139], v[176:179], v[56:59]
	v_mfma_f32_16x16x32_bf16 v[44:47], v[120:123], v[188:191], v[44:47]
	v_mfma_f32_16x16x32_bf16 v[40:43], v[136:139], v[188:191], v[40:43]
	v_mfma_f32_16x16x32_bf16 v[28:31], v[120:123], v[202:205], v[28:31]
	v_mfma_f32_16x16x32_bf16 v[24:27], v[136:139], v[202:205], v[24:27]
	v_mfma_f32_16x16x32_bf16 v[12:15], v[120:123], v[210:213], v[12:15]
	v_mfma_f32_16x16x32_bf16 v[8:11], v[136:139], v[210:213], v[8:11]
	v_mfma_f32_16x16x32_bf16 v[52:55], v[144:147], v[172:175], v[52:55]
	v_mfma_f32_16x16x32_bf16 v[48:51], v[152:155], v[172:175], v[48:51]
	v_mfma_f32_16x16x32_bf16 v[36:39], v[144:147], v[180:183], v[36:39]
	v_mfma_f32_16x16x32_bf16 v[32:35], v[152:155], v[180:183], v[32:35]
	v_mfma_f32_16x16x32_bf16 v[20:23], v[144:147], v[194:197], v[20:23]
	v_mfma_f32_16x16x32_bf16 v[16:19], v[152:155], v[194:197], v[16:19]
	v_mfma_f32_16x16x32_bf16 v[4:7], v[144:147], v[206:209], v[4:7]
	v_mfma_f32_16x16x32_bf16 v[0:3], v[152:155], v[206:209], v[0:3]
	v_mfma_f32_16x16x32_bf16 v[52:55], v[148:151], v[176:179], v[52:55]
	v_mfma_f32_16x16x32_bf16 v[48:51], v[156:159], v[176:179], v[48:51]
	v_mfma_f32_16x16x32_bf16 v[36:39], v[148:151], v[188:191], v[36:39]
	v_mfma_f32_16x16x32_bf16 v[32:35], v[156:159], v[188:191], v[32:35]
	v_mfma_f32_16x16x32_bf16 v[20:23], v[148:151], v[202:205], v[20:23]
	v_mfma_f32_16x16x32_bf16 v[16:19], v[156:159], v[202:205], v[16:19]
	v_mfma_f32_16x16x32_bf16 v[4:7], v[148:151], v[210:213], v[4:7]
	v_mfma_f32_16x16x32_bf16 v[0:3], v[156:159], v[210:213], v[0:3]
	s_setprio 0
	s_barrier
	s_add_i32 s0, 0, 0x18000
	s_add_i32 s33, 0, 0x1c000
	v_add_u32_e32 v136, s0, v185
	v_add_u32_e32 v156, s33, v185
	ds_read_b128 v[108:111], v136
	ds_read_b128 v[120:123], v136 offset:1024
	ds_read_b128 v[128:131], v136 offset:2048
	ds_read_b128 v[136:139], v136 offset:3072
	ds_read_b128 v[144:147], v156
	ds_read_b128 v[148:151], v156 offset:1024
	ds_read_b128 v[152:155], v156 offset:2048
	ds_read_b128 v[156:159], v156 offset:3072
	s_add_u32 s14, s74, 0x20000
	s_addc_u32 s15, s75, 0
	s_mov_b32 m0, s83
	v_lshl_add_u64 v[228:229], s[14:15], 0, v[166:167]
	ds_read_b128 v[172:175], v187 offset:32768
	ds_read_b128 v[176:179], v187 offset:33792
	ds_read_b128 v[180:183], v187 offset:34816
	ds_read_b128 v[188:191], v187 offset:35840
	ds_read_b128 v[194:197], v187 offset:36864
	ds_read_b128 v[202:205], v187 offset:37888
	ds_read_b128 v[206:209], v187 offset:38912
	ds_read_b128 v[210:213], v187 offset:39936
	global_load_lds_dwordx4 v[228:229], off
	v_lshl_add_u64 v[228:229], s[14:15], 0, v[162:163]
	s_mov_b32 m0, s84
	s_nop 0
	global_load_lds_dwordx4 v[228:229], off
	s_waitcnt vmcnt(8)
	s_waitcnt lgkmcnt(0)
	s_barrier
	s_setprio 1
	s_waitcnt lgkmcnt(0)
	v_mfma_f32_16x16x32_bf16 v[140:143], v[108:111], v[172:175], v[140:143]
	v_mfma_f32_16x16x32_bf16 v[132:135], v[128:131], v[172:175], v[132:135]
	v_mfma_f32_16x16x32_bf16 v[112:115], v[108:111], v[180:183], v[112:115]
	v_mfma_f32_16x16x32_bf16 v[104:107], v[128:131], v[180:183], v[104:107]
	v_mfma_f32_16x16x32_bf16 v[92:95], v[108:111], v[194:197], v[92:95]
	v_mfma_f32_16x16x32_bf16 v[88:91], v[128:131], v[194:197], v[88:91]
	v_mfma_f32_16x16x32_bf16 v[76:79], v[108:111], v[206:209], v[76:79]
	v_mfma_f32_16x16x32_bf16 v[72:75], v[128:131], v[206:209], v[72:75]
	v_mfma_f32_16x16x32_bf16 v[140:143], v[120:123], v[176:179], v[140:143]
	v_mfma_f32_16x16x32_bf16 v[132:135], v[136:139], v[176:179], v[132:135]
	v_mfma_f32_16x16x32_bf16 v[112:115], v[120:123], v[188:191], v[112:115]
	v_mfma_f32_16x16x32_bf16 v[104:107], v[136:139], v[188:191], v[104:107]
	v_mfma_f32_16x16x32_bf16 v[92:95], v[120:123], v[202:205], v[92:95]
	v_mfma_f32_16x16x32_bf16 v[88:91], v[136:139], v[202:205], v[88:91]
	v_mfma_f32_16x16x32_bf16 v[76:79], v[120:123], v[210:213], v[76:79]
	v_mfma_f32_16x16x32_bf16 v[72:75], v[136:139], v[210:213], v[72:75]
	v_mfma_f32_16x16x32_bf16 v[124:127], v[144:147], v[172:175], v[124:127]
	v_mfma_f32_16x16x32_bf16 v[116:119], v[152:155], v[172:175], v[116:119]
	v_mfma_f32_16x16x32_bf16 v[100:103], v[144:147], v[180:183], v[100:103]
	v_mfma_f32_16x16x32_bf16 v[96:99], v[152:155], v[180:183], v[96:99]
	v_mfma_f32_16x16x32_bf16 v[84:87], v[144:147], v[194:197], v[84:87]
	v_mfma_f32_16x16x32_bf16 v[80:83], v[152:155], v[194:197], v[80:83]
	v_mfma_f32_16x16x32_bf16 v[68:71], v[144:147], v[206:209], v[68:71]
	v_mfma_f32_16x16x32_bf16 v[64:67], v[152:155], v[206:209], v[64:67]
	v_mfma_f32_16x16x32_bf16 v[124:127], v[148:151], v[176:179], v[124:127]
	v_mfma_f32_16x16x32_bf16 v[116:119], v[156:159], v[176:179], v[116:119]
	v_mfma_f32_16x16x32_bf16 v[100:103], v[148:151], v[188:191], v[100:103]
	v_mfma_f32_16x16x32_bf16 v[96:99], v[156:159], v[188:191], v[96:99]
	v_mfma_f32_16x16x32_bf16 v[84:87], v[148:151], v[202:205], v[84:87]
	v_mfma_f32_16x16x32_bf16 v[80:83], v[156:159], v[202:205], v[80:83]
	v_mfma_f32_16x16x32_bf16 v[68:71], v[148:151], v[210:213], v[68:71]
	v_mfma_f32_16x16x32_bf16 v[64:67], v[156:159], v[210:213], v[64:67]
	s_setprio 0
	s_barrier
	s_add_i32 s0, s0, s80
	v_lshl_add_u64 v[214:215], v[214:215], 0, s[40:41]
	s_mov_b32 m0, s0
	ds_read_b128 v[172:175], v187 offset:49152
	ds_read_b128 v[176:179], v187 offset:50176
	ds_read_b128 v[180:183], v187 offset:51200
	ds_read_b128 v[188:191], v187 offset:52224
	ds_read_b128 v[194:197], v187 offset:53248
	ds_read_b128 v[202:205], v187 offset:54272
	ds_read_b128 v[206:209], v187 offset:55296
	ds_read_b128 v[210:213], v187 offset:56320
	global_load_lds_dwordx4 v[214:215], off
	s_add_i32 m0, s0, 0x2000
	s_add_u32 s14, s72, 0x20080
	v_lshl_add_u64 v[214:215], v[216:217], 0, s[40:41]
	s_addc_u32 s15, s73, 0
	s_add_i32 s0, s33, s80
	global_load_lds_dwordx4 v[214:215], off
	v_lshl_add_u64 v[214:215], s[14:15], 0, v[164:165]
	s_mov_b32 m0, s0
	s_nop 0
	global_load_lds_dwordx4 v[214:215], off
	v_lshl_add_u64 v[214:215], s[14:15], 0, v[160:161]
	s_add_i32 m0, s0, 0x2000
	s_nop 0
	global_load_lds_dwordx4 v[214:215], off
	v_lshl_add_u64 v[214:215], v[218:219], 0, s[40:41]
	s_mov_b32 m0, s87
	s_nop 0
	global_load_lds_dwordx4 v[214:215], off
	v_lshl_add_u64 v[214:215], v[226:227], 0, s[40:41]
	s_mov_b32 m0, s88
	s_nop 0
	global_load_lds_dwordx4 v[214:215], off
	s_waitcnt vmcnt(8)
	s_waitcnt lgkmcnt(0)
	s_barrier
	s_setprio 1
	s_waitcnt lgkmcnt(0)
	v_mfma_f32_16x16x32_bf16 v[60:63], v[108:111], v[172:175], v[60:63]
	v_mfma_f32_16x16x32_bf16 v[56:59], v[128:131], v[172:175], v[56:59]
	v_mfma_f32_16x16x32_bf16 v[44:47], v[108:111], v[180:183], v[44:47]
	v_mfma_f32_16x16x32_bf16 v[40:43], v[128:131], v[180:183], v[40:43]
	v_mfma_f32_16x16x32_bf16 v[28:31], v[108:111], v[194:197], v[28:31]
	v_mfma_f32_16x16x32_bf16 v[24:27], v[128:131], v[194:197], v[24:27]
	v_mfma_f32_16x16x32_bf16 v[12:15], v[108:111], v[206:209], v[12:15]
	v_mfma_f32_16x16x32_bf16 v[8:11], v[128:131], v[206:209], v[8:11]
	v_mfma_f32_16x16x32_bf16 v[60:63], v[120:123], v[176:179], v[60:63]
	v_mfma_f32_16x16x32_bf16 v[56:59], v[136:139], v[176:179], v[56:59]
	v_mfma_f32_16x16x32_bf16 v[44:47], v[120:123], v[188:191], v[44:47]
	v_mfma_f32_16x16x32_bf16 v[40:43], v[136:139], v[188:191], v[40:43]
	v_mfma_f32_16x16x32_bf16 v[28:31], v[120:123], v[202:205], v[28:31]
	v_mfma_f32_16x16x32_bf16 v[24:27], v[136:139], v[202:205], v[24:27]
	v_mfma_f32_16x16x32_bf16 v[12:15], v[120:123], v[210:213], v[12:15]
	v_mfma_f32_16x16x32_bf16 v[8:11], v[136:139], v[210:213], v[8:11]
	v_mfma_f32_16x16x32_bf16 v[52:55], v[144:147], v[172:175], v[52:55]
	v_mfma_f32_16x16x32_bf16 v[48:51], v[152:155], v[172:175], v[48:51]
	v_mfma_f32_16x16x32_bf16 v[36:39], v[144:147], v[180:183], v[36:39]
	v_mfma_f32_16x16x32_bf16 v[32:35], v[152:155], v[180:183], v[32:35]
	v_mfma_f32_16x16x32_bf16 v[20:23], v[144:147], v[194:197], v[20:23]
	v_mfma_f32_16x16x32_bf16 v[16:19], v[152:155], v[194:197], v[16:19]
	v_mfma_f32_16x16x32_bf16 v[4:7], v[144:147], v[206:209], v[4:7]
	v_mfma_f32_16x16x32_bf16 v[0:3], v[152:155], v[206:209], v[0:3]
	v_mfma_f32_16x16x32_bf16 v[52:55], v[148:151], v[176:179], v[52:55]
	v_mfma_f32_16x16x32_bf16 v[48:51], v[156:159], v[176:179], v[48:51]
	v_mfma_f32_16x16x32_bf16 v[36:39], v[148:151], v[188:191], v[36:39]
	v_mfma_f32_16x16x32_bf16 v[32:35], v[156:159], v[188:191], v[32:35]
	v_mfma_f32_16x16x32_bf16 v[20:23], v[148:151], v[202:205], v[20:23]
	v_mfma_f32_16x16x32_bf16 v[16:19], v[156:159], v[202:205], v[16:19]
	v_mfma_f32_16x16x32_bf16 v[4:7], v[148:151], v[210:213], v[4:7]
	v_mfma_f32_16x16x32_bf16 v[0:3], v[156:159], v[210:213], v[0:3]
	s_setprio 0
	s_barrier
	s_add_i32 s34, s34, 2
	s_add_u32 s70, s70, 0x100
	s_addc_u32 s71, s71, 0
	s_add_u32 s17, s17, 0x100
	s_addc_u32 s19, s19, 0
	s_cmp_gt_u32 s34, 5
	s_cbranch_scc0 .LBB0_116
	s_and_b64 vcc, exec, s[10:11]
	s_cbranch_vccz .LBB0_119
	s_barrier

.LBB0_234:
	s_add_u32 s30, s26, 0x100
	s_addc_u32 s31, s27, 0
	s_add_i32 s0, 0, 0x10000
	s_cmp_eq_u32 s79, 2
	s_cselect_b32 s69, s9, s31
	s_cselect_b32 s68, s8, s30
	s_cselect_b32 s67, s23, s78
	s_cselect_b32 s66, s22, s1
	s_add_i32 s33, 0, 0x14000
	v_add_u32_e32 v154, s0, v139
	v_add_u32_e32 v170, s33, v139
	ds_read_b128 v[142:145], v154
	ds_read_b128 v[146:149], v154 offset:1024
	ds_read_b128 v[150:153], v154 offset:2048
	ds_read_b128 v[154:157], v154 offset:3072
	ds_read_b128 v[158:161], v170
	ds_read_b128 v[162:165], v170 offset:1024
	ds_read_b128 v[166:169], v170 offset:2048
	ds_read_b128 v[170:173], v170 offset:3072
	v_lshl_add_u64 v[190:191], s[26:27], 0, v[134:135]
	s_add_i32 m0, s38, 0xc000
	ds_read_b128 v[174:177], v141
	ds_read_b128 v[178:181], v141 offset:1024
	ds_read_b128 v[182:185], v141 offset:2048
	ds_read_b128 v[186:189], v141 offset:3072
	ds_read_b128 v[202:205], v141 offset:4096
	ds_read_b128 v[206:209], v141 offset:5120
	ds_read_b128 v[210:213], v141 offset:6144
	ds_read_b128 v[214:217], v141 offset:7168
	global_load_lds_dwordx4 v[190:191], off
	v_lshl_add_u64 v[190:191], s[26:27], 0, v[136:137]
	s_add_i32 m0, s38, 0xe000
	s_nop 0
	global_load_lds_dwordx4 v[190:191], off
	s_waitcnt vmcnt(8)
	s_waitcnt lgkmcnt(0)
	s_barrier
	s_setprio 1
	s_waitcnt lgkmcnt(0)
	v_mfma_f32_16x16x32_bf16 v[124:127], v[142:145], v[174:177], v[124:127]
	v_mfma_f32_16x16x32_bf16 v[120:123], v[150:153], v[174:177], v[120:123]
	v_mfma_f32_16x16x32_bf16 v[116:119], v[142:145], v[182:185], v[116:119]
	v_mfma_f32_16x16x32_bf16 v[112:115], v[150:153], v[182:185], v[112:115]
	v_mfma_f32_16x16x32_bf16 v[100:103], v[142:145], v[202:205], v[100:103]
	v_mfma_f32_16x16x32_bf16 v[96:99], v[150:153], v[202:205], v[96:99]
	v_mfma_f32_16x16x32_bf16 v[84:87], v[142:145], v[210:213], v[84:87]
	v_mfma_f32_16x16x32_bf16 v[80:83], v[150:153], v[210:213], v[80:83]
	v_mfma_f32_16x16x32_bf16 v[124:127], v[146:149], v[178:181], v[124:127]
	v_mfma_f32_16x16x32_bf16 v[120:123], v[154:157], v[178:181], v[120:123]
	v_mfma_f32_16x16x32_bf16 v[116:119], v[146:149], v[186:189], v[116:119]
	v_mfma_f32_16x16x32_bf16 v[112:115], v[154:157], v[186:189], v[112:115]
	v_mfma_f32_16x16x32_bf16 v[100:103], v[146:149], v[206:209], v[100:103]
	v_mfma_f32_16x16x32_bf16 v[96:99], v[154:157], v[206:209], v[96:99]
	v_mfma_f32_16x16x32_bf16 v[84:87], v[146:149], v[214:217], v[84:87]
	v_mfma_f32_16x16x32_bf16 v[80:83], v[154:157], v[214:217], v[80:83]
	v_mfma_f32_16x16x32_bf16 v[108:111], v[158:161], v[174:177], v[108:111]
	v_mfma_f32_16x16x32_bf16 v[104:107], v[166:169], v[174:177], v[104:107]
	v_mfma_f32_16x16x32_bf16 v[92:95], v[158:161], v[182:185], v[92:95]
	v_mfma_f32_16x16x32_bf16 v[88:91], v[166:169], v[182:185], v[88:91]
	v_mfma_f32_16x16x32_bf16 v[76:79], v[158:161], v[202:205], v[76:79]
	v_mfma_f32_16x16x32_bf16 v[72:75], v[166:169], v[202:205], v[72:75]
	v_mfma_f32_16x16x32_bf16 v[68:71], v[158:161], v[210:213], v[68:71]
	v_mfma_f32_16x16x32_bf16 v[64:67], v[166:169], v[210:213], v[64:67]
	v_mfma_f32_16x16x32_bf16 v[108:111], v[162:165], v[178:181], v[108:111]
	v_mfma_f32_16x16x32_bf16 v[104:107], v[170:173], v[178:181], v[104:107]
	v_mfma_f32_16x16x32_bf16 v[92:95], v[162:165], v[186:189], v[92:95]
	v_mfma_f32_16x16x32_bf16 v[88:91], v[170:173], v[186:189], v[88:91]
	v_mfma_f32_16x16x32_bf16 v[76:79], v[162:165], v[206:209], v[76:79]
	v_mfma_f32_16x16x32_bf16 v[72:75], v[170:173], v[206:209], v[72:75]
	v_mfma_f32_16x16x32_bf16 v[68:71], v[162:165], v[214:217], v[68:71]
	v_mfma_f32_16x16x32_bf16 v[64:67], v[170:173], v[214:217], v[64:67]
	s_setprio 0
	s_barrier
	s_add_i32 s0, s0, s73
	v_lshl_add_u64 v[190:191], s[66:67], 0, v[192:193]
	s_mov_b32 m0, s0
	ds_read_b128 v[174:177], v141 offset:16384
	ds_read_b128 v[178:181], v141 offset:17408
	ds_read_b128 v[182:185], v141 offset:18432
	ds_read_b128 v[186:189], v141 offset:19456
	ds_read_b128 v[202:205], v141 offset:20480
	ds_read_b128 v[206:209], v141 offset:21504
	ds_read_b128 v[210:213], v141 offset:22528
	ds_read_b128 v[214:217], v141 offset:23552
	global_load_lds_dwordx4 v[190:191], off
	s_add_i32 m0, s0, 0x2000
	s_add_u32 s14, s66, 0x18000
	v_lshl_add_u64 v[194:195], s[66:67], 0, v[128:129]
	s_addc_u32 s15, s67, 0
	s_add_i32 s0, s33, s73
	global_load_lds_dwordx4 v[194:195], off
	v_lshl_add_u64 v[196:197], s[14:15], 0, v[192:193]
	s_mov_b32 m0, s0
	v_lshl_add_u64 v[218:219], s[68:69], 0, v[130:131]
	global_load_lds_dwordx4 v[196:197], off
	v_lshl_add_u64 v[196:197], s[14:15], 0, v[128:129]
	s_add_i32 m0, s0, 0x2000
	s_nop 0
	global_load_lds_dwordx4 v[196:197], off
	v_lshl_add_u64 v[196:197], s[68:69], 0, v[132:133]
	s_mov_b32 m0, s38
	s_nop 0
	global_load_lds_dwordx4 v[196:197], off
	s_mov_b32 m0, s52
	s_nop 0
	global_load_lds_dwordx4 v[218:219], off
	s_waitcnt vmcnt(8)
	s_waitcnt lgkmcnt(0)
	s_barrier
	s_setprio 1
	s_waitcnt lgkmcnt(0)
	v_mfma_f32_16x16x32_bf16 v[60:63], v[142:145], v[174:177], v[60:63]
	v_mfma_f32_16x16x32_bf16 v[56:59], v[150:153], v[174:177], v[56:59]
	v_mfma_f32_16x16x32_bf16 v[52:55], v[142:145], v[182:185], v[52:55]
	v_mfma_f32_16x16x32_bf16 v[48:51], v[150:153], v[182:185], v[48:51]
	v_mfma_f32_16x16x32_bf16 v[36:39], v[142:145], v[202:205], v[36:39]
	v_mfma_f32_16x16x32_bf16 v[32:35], v[150:153], v[202:205], v[32:35]
	v_mfma_f32_16x16x32_bf16 v[20:23], v[142:145], v[210:213], v[20:23]
	v_mfma_f32_16x16x32_bf16 v[16:19], v[150:153], v[210:213], v[16:19]
	v_mfma_f32_16x16x32_bf16 v[60:63], v[146:149], v[178:181], v[60:63]
	v_mfma_f32_16x16x32_bf16 v[56:59], v[154:157], v[178:181], v[56:59]
	v_mfma_f32_16x16x32_bf16 v[52:55], v[146:149], v[186:189], v[52:55]
	v_mfma_f32_16x16x32_bf16 v[48:51], v[154:157], v[186:189], v[48:51]
	v_mfma_f32_16x16x32_bf16 v[36:39], v[146:149], v[206:209], v[36:39]
	v_mfma_f32_16x16x32_bf16 v[32:35], v[154:157], v[206:209], v[32:35]
	v_mfma_f32_16x16x32_bf16 v[20:23], v[146:149], v[214:217], v[20:23]
	v_mfma_f32_16x16x32_bf16 v[16:19], v[154:157], v[214:217], v[16:19]
	v_mfma_f32_16x16x32_bf16 v[44:47], v[158:161], v[174:177], v[44:47]
	v_mfma_f32_16x16x32_bf16 v[40:43], v[166:169], v[174:177], v[40:43]
	v_mfma_f32_16x16x32_bf16 v[28:31], v[158:161], v[182:185], v[28:31]
	v_mfma_f32_16x16x32_bf16 v[24:27], v[166:169], v[182:185], v[24:27]
	v_mfma_f32_16x16x32_bf16 v[12:15], v[158:161], v[202:205], v[12:15]
	v_mfma_f32_16x16x32_bf16 v[8:11], v[166:169], v[202:205], v[8:11]
	v_mfma_f32_16x16x32_bf16 v[4:7], v[158:161], v[210:213], v[4:7]
	v_mfma_f32_16x16x32_bf16 v[0:3], v[166:169], v[210:213], v[0:3]
	v_mfma_f32_16x16x32_bf16 v[44:47], v[162:165], v[178:181], v[44:47]
	v_mfma_f32_16x16x32_bf16 v[40:43], v[170:173], v[178:181], v[40:43]
	v_mfma_f32_16x16x32_bf16 v[28:31], v[162:165], v[186:189], v[28:31]
	v_mfma_f32_16x16x32_bf16 v[24:27], v[170:173], v[186:189], v[24:27]
	v_mfma_f32_16x16x32_bf16 v[12:15], v[162:165], v[206:209], v[12:15]
	v_mfma_f32_16x16x32_bf16 v[8:11], v[170:173], v[206:209], v[8:11]
	v_mfma_f32_16x16x32_bf16 v[4:7], v[162:165], v[214:217], v[4:7]
	v_mfma_f32_16x16x32_bf16 v[0:3], v[170:173], v[214:217], v[0:3]
	s_setprio 0
	s_barrier
	s_add_i32 s0, 0, 0x18000
	s_add_i32 s26, 0, 0x1c000
	v_add_u32_e32 v154, s0, v139
	v_add_u32_e32 v170, s26, v139
	ds_read_b128 v[142:145], v154
	ds_read_b128 v[146:149], v154 offset:1024
	ds_read_b128 v[150:153], v154 offset:2048
	ds_read_b128 v[154:157], v154 offset:3072
	ds_read_b128 v[158:161], v170
	ds_read_b128 v[162:165], v170 offset:1024
	ds_read_b128 v[166:169], v170 offset:2048
	ds_read_b128 v[170:173], v170 offset:3072
	s_add_u32 s14, s68, 0x18000
	s_addc_u32 s15, s69, 0
	s_mov_b32 m0, s53
	v_lshl_add_u64 v[226:227], s[14:15], 0, v[132:133]
	ds_read_b128 v[174:177], v141 offset:32768
	ds_read_b128 v[178:181], v141 offset:33792
	ds_read_b128 v[182:185], v141 offset:34816
	ds_read_b128 v[186:189], v141 offset:35840
	ds_read_b128 v[202:205], v141 offset:36864
	ds_read_b128 v[206:209], v141 offset:37888
	ds_read_b128 v[210:213], v141 offset:38912
	ds_read_b128 v[214:217], v141 offset:39936
	global_load_lds_dwordx4 v[226:227], off
	v_lshl_add_u64 v[226:227], s[14:15], 0, v[130:131]
	s_mov_b32 m0, s74
	s_nop 0
	global_load_lds_dwordx4 v[226:227], off
	s_waitcnt vmcnt(8)
	s_waitcnt lgkmcnt(0)
	s_barrier
	s_setprio 1
	s_waitcnt lgkmcnt(0)
	v_mfma_f32_16x16x32_bf16 v[124:127], v[142:145], v[174:177], v[124:127]
	v_mfma_f32_16x16x32_bf16 v[120:123], v[150:153], v[174:177], v[120:123]
	v_mfma_f32_16x16x32_bf16 v[116:119], v[142:145], v[182:185], v[116:119]
	v_mfma_f32_16x16x32_bf16 v[112:115], v[150:153], v[182:185], v[112:115]
	v_mfma_f32_16x16x32_bf16 v[100:103], v[142:145], v[202:205], v[100:103]
	v_mfma_f32_16x16x32_bf16 v[96:99], v[150:153], v[202:205], v[96:99]
	v_mfma_f32_16x16x32_bf16 v[84:87], v[142:145], v[210:213], v[84:87]
	v_mfma_f32_16x16x32_bf16 v[80:83], v[150:153], v[210:213], v[80:83]
	v_mfma_f32_16x16x32_bf16 v[124:127], v[146:149], v[178:181], v[124:127]
	v_mfma_f32_16x16x32_bf16 v[120:123], v[154:157], v[178:181], v[120:123]
	v_mfma_f32_16x16x32_bf16 v[116:119], v[146:149], v[186:189], v[116:119]
	v_mfma_f32_16x16x32_bf16 v[112:115], v[154:157], v[186:189], v[112:115]
	v_mfma_f32_16x16x32_bf16 v[100:103], v[146:149], v[206:209], v[100:103]
	v_mfma_f32_16x16x32_bf16 v[96:99], v[154:157], v[206:209], v[96:99]
	v_mfma_f32_16x16x32_bf16 v[84:87], v[146:149], v[214:217], v[84:87]
	v_mfma_f32_16x16x32_bf16 v[80:83], v[154:157], v[214:217], v[80:83]
	v_mfma_f32_16x16x32_bf16 v[108:111], v[158:161], v[174:177], v[108:111]
	v_mfma_f32_16x16x32_bf16 v[104:107], v[166:169], v[174:177], v[104:107]
	v_mfma_f32_16x16x32_bf16 v[92:95], v[158:161], v[182:185], v[92:95]
	v_mfma_f32_16x16x32_bf16 v[88:91], v[166:169], v[182:185], v[88:91]
	v_mfma_f32_16x16x32_bf16 v[76:79], v[158:161], v[202:205], v[76:79]
	v_mfma_f32_16x16x32_bf16 v[72:75], v[166:169], v[202:205], v[72:75]
	v_mfma_f32_16x16x32_bf16 v[68:71], v[158:161], v[210:213], v[68:71]
	v_mfma_f32_16x16x32_bf16 v[64:67], v[166:169], v[210:213], v[64:67]
	v_mfma_f32_16x16x32_bf16 v[108:111], v[162:165], v[178:181], v[108:111]
	v_mfma_f32_16x16x32_bf16 v[104:107], v[170:173], v[178:181], v[104:107]
	v_mfma_f32_16x16x32_bf16 v[92:95], v[162:165], v[186:189], v[92:95]
	v_mfma_f32_16x16x32_bf16 v[88:91], v[170:173], v[186:189], v[88:91]
	v_mfma_f32_16x16x32_bf16 v[76:79], v[162:165], v[206:209], v[76:79]
	v_mfma_f32_16x16x32_bf16 v[72:75], v[170:173], v[206:209], v[72:75]
	v_mfma_f32_16x16x32_bf16 v[68:71], v[162:165], v[214:217], v[68:71]
	v_mfma_f32_16x16x32_bf16 v[64:67], v[170:173], v[214:217], v[64:67]
	s_setprio 0
	s_barrier
	s_add_i32 s0, s0, s73
	v_lshl_add_u64 v[190:191], v[190:191], 0, s[40:41]
	s_mov_b32 m0, s0
	ds_read_b128 v[174:177], v141 offset:49152
	ds_read_b128 v[178:181], v141 offset:50176
	ds_read_b128 v[182:185], v141 offset:51200
	ds_read_b128 v[186:189], v141 offset:52224
	ds_read_b128 v[202:205], v141 offset:53248
	ds_read_b128 v[206:209], v141 offset:54272
	ds_read_b128 v[210:213], v141 offset:55296
	ds_read_b128 v[214:217], v141 offset:56320
	global_load_lds_dwordx4 v[190:191], off
	s_add_i32 m0, s0, 0x2000
	s_add_u32 s14, s66, 0x18080
	v_lshl_add_u64 v[190:191], v[194:195], 0, s[40:41]
	s_addc_u32 s15, s67, 0
	s_add_i32 s0, s26, s73
	global_load_lds_dwordx4 v[190:191], off
	v_lshl_add_u64 v[190:191], s[14:15], 0, v[192:193]
	s_mov_b32 m0, s0
	s_nop 0
	global_load_lds_dwordx4 v[190:191], off
	v_lshl_add_u64 v[190:191], s[14:15], 0, v[128:129]
	s_add_i32 m0, s0, 0x2000
	s_nop 0
	global_load_lds_dwordx4 v[190:191], off
	v_lshl_add_u64 v[190:191], v[196:197], 0, s[40:41]
	s_mov_b32 m0, s35
	s_nop 0
	global_load_lds_dwordx4 v[190:191], off
	v_lshl_add_u64 v[190:191], v[218:219], 0, s[40:41]
	s_mov_b32 m0, s46
	s_nop 0
	global_load_lds_dwordx4 v[190:191], off
	s_waitcnt vmcnt(8)
	s_waitcnt lgkmcnt(0)
	s_barrier
	s_setprio 1
	s_waitcnt lgkmcnt(0)
	v_mfma_f32_16x16x32_bf16 v[60:63], v[142:145], v[174:177], v[60:63]
	v_mfma_f32_16x16x32_bf16 v[56:59], v[150:153], v[174:177], v[56:59]
	v_mfma_f32_16x16x32_bf16 v[52:55], v[142:145], v[182:185], v[52:55]
	v_mfma_f32_16x16x32_bf16 v[48:51], v[150:153], v[182:185], v[48:51]
	v_mfma_f32_16x16x32_bf16 v[36:39], v[142:145], v[202:205], v[36:39]
	v_mfma_f32_16x16x32_bf16 v[32:35], v[150:153], v[202:205], v[32:35]
	v_mfma_f32_16x16x32_bf16 v[20:23], v[142:145], v[210:213], v[20:23]
	v_mfma_f32_16x16x32_bf16 v[16:19], v[150:153], v[210:213], v[16:19]
	v_mfma_f32_16x16x32_bf16 v[60:63], v[146:149], v[178:181], v[60:63]
	v_mfma_f32_16x16x32_bf16 v[56:59], v[154:157], v[178:181], v[56:59]
	v_mfma_f32_16x16x32_bf16 v[52:55], v[146:149], v[186:189], v[52:55]
	v_mfma_f32_16x16x32_bf16 v[48:51], v[154:157], v[186:189], v[48:51]
	v_mfma_f32_16x16x32_bf16 v[36:39], v[146:149], v[206:209], v[36:39]
	v_mfma_f32_16x16x32_bf16 v[32:35], v[154:157], v[206:209], v[32:35]
	v_mfma_f32_16x16x32_bf16 v[20:23], v[146:149], v[214:217], v[20:23]
	v_mfma_f32_16x16x32_bf16 v[16:19], v[154:157], v[214:217], v[16:19]
	v_mfma_f32_16x16x32_bf16 v[44:47], v[158:161], v[174:177], v[44:47]
	v_mfma_f32_16x16x32_bf16 v[40:43], v[166:169], v[174:177], v[40:43]
	v_mfma_f32_16x16x32_bf16 v[28:31], v[158:161], v[182:185], v[28:31]
	v_mfma_f32_16x16x32_bf16 v[24:27], v[166:169], v[182:185], v[24:27]
	v_mfma_f32_16x16x32_bf16 v[12:15], v[158:161], v[202:205], v[12:15]
	v_mfma_f32_16x16x32_bf16 v[8:11], v[166:169], v[202:205], v[8:11]
	v_mfma_f32_16x16x32_bf16 v[4:7], v[158:161], v[210:213], v[4:7]
	v_mfma_f32_16x16x32_bf16 v[0:3], v[166:169], v[210:213], v[0:3]
	v_mfma_f32_16x16x32_bf16 v[44:47], v[162:165], v[178:181], v[44:47]
	v_mfma_f32_16x16x32_bf16 v[40:43], v[170:173], v[178:181], v[40:43]
	v_mfma_f32_16x16x32_bf16 v[28:31], v[162:165], v[186:189], v[28:31]
	v_mfma_f32_16x16x32_bf16 v[24:27], v[170:173], v[186:189], v[24:27]
	v_mfma_f32_16x16x32_bf16 v[12:15], v[162:165], v[206:209], v[12:15]
	v_mfma_f32_16x16x32_bf16 v[8:11], v[170:173], v[206:209], v[8:11]
	v_mfma_f32_16x16x32_bf16 v[4:7], v[162:165], v[214:217], v[4:7]
	v_mfma_f32_16x16x32_bf16 v[0:3], v[170:173], v[214:217], v[0:3]
	s_setprio 0
	s_barrier
	s_add_i32 s79, s79, 2
	s_add_u32 s1, s1, 0x100
	s_addc_u32 s78, s78, 0
	s_cmp_gt_u32 s79, 3
	s_mov_b64 s[26:27], s[30:31]
	s_cbranch_scc0 .LBB0_234
	s_and_b64 vcc, exec, s[20:21]
	s_cbranch_vccz .LBB0_237
	s_barrier

.LBB0_250:
	s_add_u32 s33, s68, s1
	s_addc_u32 s50, s69, 0
	s_add_u32 s0, s33, 0x100
	s_addc_u32 s51, s50, 0
	s_and_b64 s[14:15], s[78:79], exec
	s_cselect_b32 s83, s65, s51
	s_cselect_b32 s82, s71, s0
	s_add_u32 s0, s30, s1
	s_addc_u32 s1, s31, 0
	s_add_u32 s14, s0, 0x100
	s_addc_u32 s15, s1, 0
	s_add_i32 s51, 0, 0x10000
	s_and_b64 s[0:1], s[78:79], exec
	s_cselect_b32 s85, s67, s15
	s_cselect_b32 s84, s93, s14
	s_add_i32 s79, 0, 0x14000
	s_add_u32 s88, s33, 0x10080
	s_addc_u32 s89, s50, 0
	s_add_i32 s33, s51, s91
	s_add_i32 m0, s42, 0xc000
	s_add_i32 s23, s42, 0xe000
	s_add_i32 s96, s33, 0x2000
	s_add_u32 s86, s84, 0x10000
	v_add_u32_e32 v150, s51, v135
	v_add_u32_e32 v166, s79, v135
	s_addc_u32 s87, s85, 0
	s_add_i32 s15, s79, s91
	ds_read_b128 v[138:141], v150
	ds_read_b128 v[142:145], v150 offset:1024
	ds_read_b128 v[146:149], v150 offset:2048
	ds_read_b128 v[150:153], v150 offset:3072
	ds_read_b128 v[154:157], v166
	ds_read_b128 v[158:161], v166 offset:1024
	ds_read_b128 v[162:165], v166 offset:2048
	ds_read_b128 v[166:169], v166 offset:3072
	s_add_i32 s14, s15, 0x2000
	s_add_i32 vcc_lo, 0, 0x18000
	s_add_i32 vcc_hi, 0, 0x1c000
	s_add_u32 s80, s82, 0x10000
	s_addc_u32 s81, s83, 0
	s_add_i32 s1, vcc_lo, s91
	s_add_i32 s0, s1, 0x2000
	s_add_u32 s78, s84, 0x10080
	s_addc_u32 s79, s85, 0
	s_add_i32 s51, vcc_hi, s91
	s_add_i32 s50, s51, 0x2000
	v_lshl_add_u64 v[190:191], s[88:89], 0, v[132:133]
	ds_read_b128 v[170:173], v137
	ds_read_b128 v[174:177], v137 offset:1024
	ds_read_b128 v[178:181], v137 offset:2048
	ds_read_b128 v[182:185], v137 offset:3072
	ds_read_b128 v[186:189], v137 offset:4096
	ds_read_b128 v[202:205], v137 offset:5120
	ds_read_b128 v[206:209], v137 offset:6144
	ds_read_b128 v[210:213], v137 offset:7168
	global_load_lds_dwordx4 v[190:191], off
	v_lshl_add_u64 v[190:191], s[88:89], 0, v[130:131]
	s_mov_b32 m0, s23
	s_nop 0
	global_load_lds_dwordx4 v[190:191], off
	s_waitcnt vmcnt(8)
	s_waitcnt lgkmcnt(0)
	s_barrier
	s_setprio 1
	s_waitcnt lgkmcnt(0)
	v_mfma_f32_16x16x32_bf16 v[124:127], v[138:141], v[170:173], v[124:127]
	v_mfma_f32_16x16x32_bf16 v[120:123], v[146:149], v[170:173], v[120:123]
	v_mfma_f32_16x16x32_bf16 v[116:119], v[138:141], v[178:181], v[116:119]
	v_mfma_f32_16x16x32_bf16 v[112:115], v[146:149], v[178:181], v[112:115]
	v_mfma_f32_16x16x32_bf16 v[100:103], v[138:141], v[186:189], v[100:103]
	v_mfma_f32_16x16x32_bf16 v[96:99], v[146:149], v[186:189], v[96:99]
	v_mfma_f32_16x16x32_bf16 v[84:87], v[138:141], v[206:209], v[84:87]
	v_mfma_f32_16x16x32_bf16 v[80:83], v[146:149], v[206:209], v[80:83]
	v_mfma_f32_16x16x32_bf16 v[124:127], v[142:145], v[174:177], v[124:127]
	v_mfma_f32_16x16x32_bf16 v[120:123], v[150:153], v[174:177], v[120:123]
	v_mfma_f32_16x16x32_bf16 v[116:119], v[142:145], v[182:185], v[116:119]
	v_mfma_f32_16x16x32_bf16 v[112:115], v[150:153], v[182:185], v[112:115]
	v_mfma_f32_16x16x32_bf16 v[100:103], v[142:145], v[202:205], v[100:103]
	v_mfma_f32_16x16x32_bf16 v[96:99], v[150:153], v[202:205], v[96:99]
	v_mfma_f32_16x16x32_bf16 v[84:87], v[142:145], v[210:213], v[84:87]
	v_mfma_f32_16x16x32_bf16 v[80:83], v[150:153], v[210:213], v[80:83]
	v_mfma_f32_16x16x32_bf16 v[108:111], v[154:157], v[170:173], v[108:111]
	v_mfma_f32_16x16x32_bf16 v[104:107], v[162:165], v[170:173], v[104:107]
	v_mfma_f32_16x16x32_bf16 v[92:95], v[154:157], v[178:181], v[92:95]
	v_mfma_f32_16x16x32_bf16 v[88:91], v[162:165], v[178:181], v[88:91]
	v_mfma_f32_16x16x32_bf16 v[76:79], v[154:157], v[186:189], v[76:79]
	v_mfma_f32_16x16x32_bf16 v[72:75], v[162:165], v[186:189], v[72:75]
	v_mfma_f32_16x16x32_bf16 v[68:71], v[154:157], v[206:209], v[68:71]
	v_mfma_f32_16x16x32_bf16 v[64:67], v[162:165], v[206:209], v[64:67]
	v_mfma_f32_16x16x32_bf16 v[108:111], v[158:161], v[174:177], v[108:111]
	v_mfma_f32_16x16x32_bf16 v[104:107], v[166:169], v[174:177], v[104:107]
	v_mfma_f32_16x16x32_bf16 v[92:95], v[158:161], v[182:185], v[92:95]
	v_mfma_f32_16x16x32_bf16 v[88:91], v[166:169], v[182:185], v[88:91]
	v_mfma_f32_16x16x32_bf16 v[76:79], v[158:161], v[202:205], v[76:79]
	v_mfma_f32_16x16x32_bf16 v[72:75], v[166:169], v[202:205], v[72:75]
	v_mfma_f32_16x16x32_bf16 v[68:71], v[158:161], v[210:213], v[68:71]
	v_mfma_f32_16x16x32_bf16 v[64:67], v[166:169], v[210:213], v[64:67]
	s_setprio 0
	s_barrier
	s_mov_b32 m0, s33
	v_lshl_add_u64 v[190:191], s[84:85], 0, v[192:193]
	ds_read_b128 v[170:173], v137 offset:16384
	ds_read_b128 v[174:177], v137 offset:17408
	ds_read_b128 v[178:181], v137 offset:18432
	ds_read_b128 v[182:185], v137 offset:19456
	ds_read_b128 v[186:189], v137 offset:20480
	ds_read_b128 v[202:205], v137 offset:21504
	ds_read_b128 v[206:209], v137 offset:22528
	ds_read_b128 v[210:213], v137 offset:23552
	global_load_lds_dwordx4 v[190:191], off
	v_lshl_add_u64 v[194:195], s[84:85], 0, v[128:129]
	s_mov_b32 m0, s96
	v_lshl_add_u64 v[196:197], s[86:87], 0, v[192:193]
	global_load_lds_dwordx4 v[194:195], off
	s_mov_b32 m0, s15
	v_lshl_add_u64 v[214:215], s[82:83], 0, v[130:131]
	global_load_lds_dwordx4 v[196:197], off
	v_lshl_add_u64 v[196:197], s[86:87], 0, v[128:129]
	s_mov_b32 m0, s14
	s_nop 0
	global_load_lds_dwordx4 v[196:197], off
	v_lshl_add_u64 v[196:197], s[82:83], 0, v[132:133]
	s_mov_b32 m0, s42
	s_nop 0
	global_load_lds_dwordx4 v[196:197], off
	s_mov_b32 m0, s27
	s_nop 0
	global_load_lds_dwordx4 v[214:215], off
	s_waitcnt vmcnt(8)
	s_waitcnt lgkmcnt(0)
	s_barrier
	s_setprio 1
	s_waitcnt lgkmcnt(0)
	v_mfma_f32_16x16x32_bf16 v[60:63], v[138:141], v[170:173], v[60:63]
	v_mfma_f32_16x16x32_bf16 v[56:59], v[146:149], v[170:173], v[56:59]
	v_mfma_f32_16x16x32_bf16 v[52:55], v[138:141], v[178:181], v[52:55]
	v_mfma_f32_16x16x32_bf16 v[48:51], v[146:149], v[178:181], v[48:51]
	v_mfma_f32_16x16x32_bf16 v[36:39], v[138:141], v[186:189], v[36:39]
	v_mfma_f32_16x16x32_bf16 v[32:35], v[146:149], v[186:189], v[32:35]
	v_mfma_f32_16x16x32_bf16 v[20:23], v[138:141], v[206:209], v[20:23]
	v_mfma_f32_16x16x32_bf16 v[16:19], v[146:149], v[206:209], v[16:19]
	v_mfma_f32_16x16x32_bf16 v[60:63], v[142:145], v[174:177], v[60:63]
	v_mfma_f32_16x16x32_bf16 v[56:59], v[150:153], v[174:177], v[56:59]
	v_mfma_f32_16x16x32_bf16 v[52:55], v[142:145], v[182:185], v[52:55]
	v_mfma_f32_16x16x32_bf16 v[48:51], v[150:153], v[182:185], v[48:51]
	v_mfma_f32_16x16x32_bf16 v[36:39], v[142:145], v[202:205], v[36:39]
	v_mfma_f32_16x16x32_bf16 v[32:35], v[150:153], v[202:205], v[32:35]
	v_mfma_f32_16x16x32_bf16 v[20:23], v[142:145], v[210:213], v[20:23]
	v_mfma_f32_16x16x32_bf16 v[16:19], v[150:153], v[210:213], v[16:19]
	v_mfma_f32_16x16x32_bf16 v[44:47], v[154:157], v[170:173], v[44:47]
	v_mfma_f32_16x16x32_bf16 v[40:43], v[162:165], v[170:173], v[40:43]
	v_mfma_f32_16x16x32_bf16 v[28:31], v[154:157], v[178:181], v[28:31]
	v_mfma_f32_16x16x32_bf16 v[24:27], v[162:165], v[178:181], v[24:27]
	v_mfma_f32_16x16x32_bf16 v[12:15], v[154:157], v[186:189], v[12:15]
	v_mfma_f32_16x16x32_bf16 v[8:11], v[162:165], v[186:189], v[8:11]
	v_mfma_f32_16x16x32_bf16 v[4:7], v[154:157], v[206:209], v[4:7]
	v_mfma_f32_16x16x32_bf16 v[0:3], v[162:165], v[206:209], v[0:3]
	v_mfma_f32_16x16x32_bf16 v[44:47], v[158:161], v[174:177], v[44:47]
	v_mfma_f32_16x16x32_bf16 v[40:43], v[166:169], v[174:177], v[40:43]
	v_mfma_f32_16x16x32_bf16 v[28:31], v[158:161], v[182:185], v[28:31]
	v_mfma_f32_16x16x32_bf16 v[24:27], v[166:169], v[182:185], v[24:27]
	v_mfma_f32_16x16x32_bf16 v[12:15], v[158:161], v[202:205], v[12:15]
	v_mfma_f32_16x16x32_bf16 v[8:11], v[166:169], v[202:205], v[8:11]
	v_mfma_f32_16x16x32_bf16 v[4:7], v[158:161], v[210:213], v[4:7]
	v_mfma_f32_16x16x32_bf16 v[0:3], v[166:169], v[210:213], v[0:3]
	s_setprio 0
	s_barrier
	v_add_u32_e32 v150, vcc_lo, v135
	v_add_u32_e32 v166, vcc_hi, v135
	ds_read_b128 v[138:141], v150
	ds_read_b128 v[142:145], v150 offset:1024
	ds_read_b128 v[146:149], v150 offset:2048
	ds_read_b128 v[150:153], v150 offset:3072
	ds_read_b128 v[154:157], v166
	ds_read_b128 v[158:161], v166 offset:1024
	ds_read_b128 v[162:165], v166 offset:2048
	ds_read_b128 v[166:169], v166 offset:3072
	s_mov_b32 m0, s52
	v_lshl_add_u64 v[216:217], s[80:81], 0, v[132:133]
	ds_read_b128 v[170:173], v137 offset:32768
	ds_read_b128 v[174:177], v137 offset:33792
	ds_read_b128 v[178:181], v137 offset:34816
	ds_read_b128 v[182:185], v137 offset:35840
	ds_read_b128 v[186:189], v137 offset:36864
	ds_read_b128 v[202:205], v137 offset:37888
	ds_read_b128 v[206:209], v137 offset:38912
	ds_read_b128 v[210:213], v137 offset:39936
	global_load_lds_dwordx4 v[216:217], off
	v_lshl_add_u64 v[216:217], s[80:81], 0, v[130:131]
	s_mov_b32 m0, s53
	s_nop 0
	global_load_lds_dwordx4 v[216:217], off
	s_waitcnt vmcnt(8)
	s_waitcnt lgkmcnt(0)
	s_barrier
	s_setprio 1
	s_waitcnt lgkmcnt(0)
	v_mfma_f32_16x16x32_bf16 v[124:127], v[138:141], v[170:173], v[124:127]
	v_mfma_f32_16x16x32_bf16 v[120:123], v[146:149], v[170:173], v[120:123]
	v_mfma_f32_16x16x32_bf16 v[116:119], v[138:141], v[178:181], v[116:119]
	v_mfma_f32_16x16x32_bf16 v[112:115], v[146:149], v[178:181], v[112:115]
	v_mfma_f32_16x16x32_bf16 v[100:103], v[138:141], v[186:189], v[100:103]
	v_mfma_f32_16x16x32_bf16 v[96:99], v[146:149], v[186:189], v[96:99]
	v_mfma_f32_16x16x32_bf16 v[84:87], v[138:141], v[206:209], v[84:87]
	v_mfma_f32_16x16x32_bf16 v[80:83], v[146:149], v[206:209], v[80:83]
	v_mfma_f32_16x16x32_bf16 v[124:127], v[142:145], v[174:177], v[124:127]
	v_mfma_f32_16x16x32_bf16 v[120:123], v[150:153], v[174:177], v[120:123]
	v_mfma_f32_16x16x32_bf16 v[116:119], v[142:145], v[182:185], v[116:119]
	v_mfma_f32_16x16x32_bf16 v[112:115], v[150:153], v[182:185], v[112:115]
	v_mfma_f32_16x16x32_bf16 v[100:103], v[142:145], v[202:205], v[100:103]
	v_mfma_f32_16x16x32_bf16 v[96:99], v[150:153], v[202:205], v[96:99]
	v_mfma_f32_16x16x32_bf16 v[84:87], v[142:145], v[210:213], v[84:87]
	v_mfma_f32_16x16x32_bf16 v[80:83], v[150:153], v[210:213], v[80:83]
	v_mfma_f32_16x16x32_bf16 v[108:111], v[154:157], v[170:173], v[108:111]
	v_mfma_f32_16x16x32_bf16 v[104:107], v[162:165], v[170:173], v[104:107]
	v_mfma_f32_16x16x32_bf16 v[92:95], v[154:157], v[178:181], v[92:95]
	v_mfma_f32_16x16x32_bf16 v[88:91], v[162:165], v[178:181], v[88:91]
	v_mfma_f32_16x16x32_bf16 v[76:79], v[154:157], v[186:189], v[76:79]
	v_mfma_f32_16x16x32_bf16 v[72:75], v[162:165], v[186:189], v[72:75]
	v_mfma_f32_16x16x32_bf16 v[68:71], v[154:157], v[206:209], v[68:71]
	v_mfma_f32_16x16x32_bf16 v[64:67], v[162:165], v[206:209], v[64:67]
	v_mfma_f32_16x16x32_bf16 v[108:111], v[158:161], v[174:177], v[108:111]
	v_mfma_f32_16x16x32_bf16 v[104:107], v[166:169], v[174:177], v[104:107]
	v_mfma_f32_16x16x32_bf16 v[92:95], v[158:161], v[182:185], v[92:95]
	v_mfma_f32_16x16x32_bf16 v[88:91], v[166:169], v[182:185], v[88:91]
	v_mfma_f32_16x16x32_bf16 v[76:79], v[158:161], v[202:205], v[76:79]
	v_mfma_f32_16x16x32_bf16 v[72:75], v[166:169], v[202:205], v[72:75]
	v_mfma_f32_16x16x32_bf16 v[68:71], v[158:161], v[210:213], v[68:71]
	v_mfma_f32_16x16x32_bf16 v[64:67], v[166:169], v[210:213], v[64:67]
	s_setprio 0
	s_barrier
	s_mov_b32 m0, s1
	v_lshl_add_u64 v[190:191], v[190:191], 0, s[40:41]
	ds_read_b128 v[170:173], v137 offset:49152
	ds_read_b128 v[174:177], v137 offset:50176
	ds_read_b128 v[178:181], v137 offset:51200
	ds_read_b128 v[182:185], v137 offset:52224
	ds_read_b128 v[186:189], v137 offset:53248
	ds_read_b128 v[202:205], v137 offset:54272
	ds_read_b128 v[206:209], v137 offset:55296
	ds_read_b128 v[210:213], v137 offset:56320
	global_load_lds_dwordx4 v[190:191], off
	v_lshl_add_u64 v[190:191], v[194:195], 0, s[40:41]
	s_mov_b32 m0, s0
	s_nop 0
	global_load_lds_dwordx4 v[190:191], off
	v_lshl_add_u64 v[190:191], s[78:79], 0, v[192:193]
	s_mov_b32 m0, s51
	s_nop 0
	global_load_lds_dwordx4 v[190:191], off
	v_lshl_add_u64 v[190:191], s[78:79], 0, v[128:129]
	s_mov_b32 m0, s50
	s_nop 0
	global_load_lds_dwordx4 v[190:191], off
	v_lshl_add_u64 v[190:191], v[196:197], 0, s[40:41]
	s_mov_b32 m0, s46
	s_nop 0
	global_load_lds_dwordx4 v[190:191], off
	v_lshl_add_u64 v[190:191], v[214:215], 0, s[40:41]
	s_mov_b32 m0, s35
	s_nop 0
	global_load_lds_dwordx4 v[190:191], off
	s_waitcnt vmcnt(8)
	s_waitcnt lgkmcnt(0)
	s_barrier
	s_setprio 1
	s_waitcnt lgkmcnt(0)
	v_mfma_f32_16x16x32_bf16 v[60:63], v[138:141], v[170:173], v[60:63]
	v_mfma_f32_16x16x32_bf16 v[56:59], v[146:149], v[170:173], v[56:59]
	v_mfma_f32_16x16x32_bf16 v[52:55], v[138:141], v[178:181], v[52:55]
	v_mfma_f32_16x16x32_bf16 v[48:51], v[146:149], v[178:181], v[48:51]
	v_mfma_f32_16x16x32_bf16 v[36:39], v[138:141], v[186:189], v[36:39]
	v_mfma_f32_16x16x32_bf16 v[32:35], v[146:149], v[186:189], v[32:35]
	v_mfma_f32_16x16x32_bf16 v[20:23], v[138:141], v[206:209], v[20:23]
	v_mfma_f32_16x16x32_bf16 v[16:19], v[146:149], v[206:209], v[16:19]
	v_mfma_f32_16x16x32_bf16 v[60:63], v[142:145], v[174:177], v[60:63]
	v_mfma_f32_16x16x32_bf16 v[56:59], v[150:153], v[174:177], v[56:59]
	v_mfma_f32_16x16x32_bf16 v[52:55], v[142:145], v[182:185], v[52:55]
	v_mfma_f32_16x16x32_bf16 v[48:51], v[150:153], v[182:185], v[48:51]
	v_mfma_f32_16x16x32_bf16 v[36:39], v[142:145], v[202:205], v[36:39]
	v_mfma_f32_16x16x32_bf16 v[32:35], v[150:153], v[202:205], v[32:35]
	v_mfma_f32_16x16x32_bf16 v[20:23], v[142:145], v[210:213], v[20:23]
	v_mfma_f32_16x16x32_bf16 v[16:19], v[150:153], v[210:213], v[16:19]
	v_mfma_f32_16x16x32_bf16 v[44:47], v[154:157], v[170:173], v[44:47]
	v_mfma_f32_16x16x32_bf16 v[40:43], v[162:165], v[170:173], v[40:43]
	v_mfma_f32_16x16x32_bf16 v[28:31], v[154:157], v[178:181], v[28:31]
	v_mfma_f32_16x16x32_bf16 v[24:27], v[162:165], v[178:181], v[24:27]
	v_mfma_f32_16x16x32_bf16 v[12:15], v[154:157], v[186:189], v[12:15]
	v_mfma_f32_16x16x32_bf16 v[8:11], v[162:165], v[186:189], v[8:11]
	v_mfma_f32_16x16x32_bf16 v[4:7], v[154:157], v[206:209], v[4:7]
	v_mfma_f32_16x16x32_bf16 v[0:3], v[162:165], v[206:209], v[0:3]
	v_mfma_f32_16x16x32_bf16 v[44:47], v[158:161], v[174:177], v[44:47]
	v_mfma_f32_16x16x32_bf16 v[40:43], v[166:169], v[174:177], v[40:43]
	v_mfma_f32_16x16x32_bf16 v[28:31], v[158:161], v[182:185], v[28:31]
	v_mfma_f32_16x16x32_bf16 v[24:27], v[166:169], v[182:185], v[24:27]
	v_mfma_f32_16x16x32_bf16 v[12:15], v[158:161], v[202:205], v[12:15]
	v_mfma_f32_16x16x32_bf16 v[8:11], v[166:169], v[202:205], v[8:11]
	v_mfma_f32_16x16x32_bf16 v[4:7], v[158:161], v[210:213], v[4:7]
	v_mfma_f32_16x16x32_bf16 v[0:3], v[166:169], v[210:213], v[0:3]
	s_setprio 0
	s_barrier
	s_movk_i32 s1, 0x100
	s_andn2_b64 vcc, exec, s[76:77]
	s_mov_b64 s[78:79], -1
	s_mov_b64 s[76:77], 0
	s_cbranch_vccz .LBB0_250
	s_and_b64 vcc, exec, s[20:21]
	s_cbranch_vccz .LBB0_253
	s_barrier

.LBB0_278:
	s_add_u32 s0, s82, 0xfffc0080
	s_addc_u32 s14, s83, -1
	s_add_i32 s15, 0, 0x10000
	s_cmp_eq_u32 s93, 12
	s_cselect_b32 s87, s77, s14
	s_cselect_b32 s86, s89, s0
	v_add_u32_e32 v143, s15, v140
	s_cselect_b32 s85, s1, s91
	s_cselect_b32 s84, s23, s90
	s_add_i32 s0, 0, 0x14000
	ds_read_b128 v[144:147], v143
	ds_read_b128 v[148:151], v143 offset:1024
	ds_read_b128 v[152:155], v143 offset:2048
	ds_read_b128 v[156:159], v143 offset:3072
	v_add_u32_e32 v143, s0, v140
	ds_read_b128 v[160:163], v143
	ds_read_b128 v[164:167], v143 offset:1024
	ds_read_b128 v[168:171], v143 offset:2048
	ds_read_b128 v[172:175], v143 offset:3072
	v_lshl_add_u64 v[194:195], s[82:83], 0, v[134:135]
	s_add_i32 m0, s19, 0xc000
	ds_read_b128 v[176:179], v142
	ds_read_b128 v[180:183], v142 offset:1024
	ds_read_b128 v[184:187], v142 offset:2048
	ds_read_b128 v[188:191], v142 offset:3072
	ds_read_b128 v[202:205], v142 offset:4096
	ds_read_b128 v[206:209], v142 offset:5120
	ds_read_b128 v[210:213], v142 offset:6144
	ds_read_b128 v[214:217], v142 offset:7168
	global_load_lds_dwordx4 v[194:195], off
	v_lshl_add_u64 v[194:195], s[82:83], 0, v[136:137]
	s_add_i32 m0, s19, 0xe000
	s_nop 0
	global_load_lds_dwordx4 v[194:195], off
	s_waitcnt vmcnt(8)
	s_waitcnt lgkmcnt(0)
	s_barrier
	s_setprio 1
	s_waitcnt lgkmcnt(0)
	v_mfma_f32_16x16x32_bf16 v[124:127], v[144:147], v[176:179], v[124:127]
	v_mfma_f32_16x16x32_bf16 v[120:123], v[152:155], v[176:179], v[120:123]
	v_mfma_f32_16x16x32_bf16 v[116:119], v[144:147], v[184:187], v[116:119]
	v_mfma_f32_16x16x32_bf16 v[112:115], v[152:155], v[184:187], v[112:115]
	v_mfma_f32_16x16x32_bf16 v[100:103], v[144:147], v[202:205], v[100:103]
	v_mfma_f32_16x16x32_bf16 v[96:99], v[152:155], v[202:205], v[96:99]
	v_mfma_f32_16x16x32_bf16 v[84:87], v[144:147], v[210:213], v[84:87]
	v_mfma_f32_16x16x32_bf16 v[80:83], v[152:155], v[210:213], v[80:83]
	v_mfma_f32_16x16x32_bf16 v[124:127], v[148:151], v[180:183], v[124:127]
	v_mfma_f32_16x16x32_bf16 v[120:123], v[156:159], v[180:183], v[120:123]
	v_mfma_f32_16x16x32_bf16 v[116:119], v[148:151], v[188:191], v[116:119]
	v_mfma_f32_16x16x32_bf16 v[112:115], v[156:159], v[188:191], v[112:115]
	v_mfma_f32_16x16x32_bf16 v[100:103], v[148:151], v[206:209], v[100:103]
	v_mfma_f32_16x16x32_bf16 v[96:99], v[156:159], v[206:209], v[96:99]
	v_mfma_f32_16x16x32_bf16 v[84:87], v[148:151], v[214:217], v[84:87]
	v_mfma_f32_16x16x32_bf16 v[80:83], v[156:159], v[214:217], v[80:83]
	v_mfma_f32_16x16x32_bf16 v[108:111], v[160:163], v[176:179], v[108:111]
	v_mfma_f32_16x16x32_bf16 v[104:107], v[168:171], v[176:179], v[104:107]
	v_mfma_f32_16x16x32_bf16 v[92:95], v[160:163], v[184:187], v[92:95]
	v_mfma_f32_16x16x32_bf16 v[88:91], v[168:171], v[184:187], v[88:91]
	v_mfma_f32_16x16x32_bf16 v[76:79], v[160:163], v[202:205], v[76:79]
	v_mfma_f32_16x16x32_bf16 v[72:75], v[168:171], v[202:205], v[72:75]
	v_mfma_f32_16x16x32_bf16 v[68:71], v[160:163], v[210:213], v[68:71]
	v_mfma_f32_16x16x32_bf16 v[64:67], v[168:171], v[210:213], v[64:67]
	v_mfma_f32_16x16x32_bf16 v[108:111], v[164:167], v[180:183], v[108:111]
	v_mfma_f32_16x16x32_bf16 v[104:107], v[172:175], v[180:183], v[104:107]
	v_mfma_f32_16x16x32_bf16 v[92:95], v[164:167], v[188:191], v[92:95]
	v_mfma_f32_16x16x32_bf16 v[88:91], v[172:175], v[188:191], v[88:91]
	v_mfma_f32_16x16x32_bf16 v[76:79], v[164:167], v[206:209], v[76:79]
	v_mfma_f32_16x16x32_bf16 v[72:75], v[172:175], v[206:209], v[72:75]
	v_mfma_f32_16x16x32_bf16 v[68:71], v[164:167], v[214:217], v[68:71]
	v_mfma_f32_16x16x32_bf16 v[64:67], v[172:175], v[214:217], v[64:67]
	s_setprio 0
	s_barrier
	s_add_i32 s14, s15, s61
	v_lshl_add_u64 v[194:195], s[84:85], 0, v[192:193]
	s_mov_b32 m0, s14
	ds_read_b128 v[176:179], v142 offset:16384
	ds_read_b128 v[180:183], v142 offset:17408
	ds_read_b128 v[184:187], v142 offset:18432
	ds_read_b128 v[188:191], v142 offset:19456
	ds_read_b128 v[202:205], v142 offset:20480
	ds_read_b128 v[206:209], v142 offset:21504
	ds_read_b128 v[210:213], v142 offset:22528
	ds_read_b128 v[214:217], v142 offset:23552
	global_load_lds_dwordx4 v[194:195], off
	s_add_i32 m0, s14, 0x2000
	s_add_u32 s14, s84, 0x40000
	v_lshl_add_u64 v[196:197], s[84:85], 0, v[128:129]
	s_addc_u32 s15, s85, 0
	s_add_i32 s0, s0, s61
	global_load_lds_dwordx4 v[196:197], off
	v_lshl_add_u64 v[218:219], s[14:15], 0, v[192:193]
	s_mov_b32 m0, s0
	v_lshl_add_u64 v[226:227], s[86:87], 0, v[130:131]
	global_load_lds_dwordx4 v[218:219], off
	v_lshl_add_u64 v[218:219], s[14:15], 0, v[128:129]
	s_add_i32 m0, s0, 0x2000
	s_nop 0
	global_load_lds_dwordx4 v[218:219], off
	v_lshl_add_u64 v[218:219], s[86:87], 0, v[132:133]
	s_mov_b32 m0, s19
	s_nop 0
	global_load_lds_dwordx4 v[218:219], off
	s_mov_b32 m0, s52
	s_nop 0
	global_load_lds_dwordx4 v[226:227], off
	s_waitcnt vmcnt(8)
	s_waitcnt lgkmcnt(0)
	s_barrier
	s_setprio 1
	s_waitcnt lgkmcnt(0)
	v_mfma_f32_16x16x32_bf16 v[60:63], v[144:147], v[176:179], v[60:63]
	v_mfma_f32_16x16x32_bf16 v[56:59], v[152:155], v[176:179], v[56:59]
	v_mfma_f32_16x16x32_bf16 v[52:55], v[144:147], v[184:187], v[52:55]
	v_mfma_f32_16x16x32_bf16 v[48:51], v[152:155], v[184:187], v[48:51]
	v_mfma_f32_16x16x32_bf16 v[36:39], v[144:147], v[202:205], v[36:39]
	v_mfma_f32_16x16x32_bf16 v[32:35], v[152:155], v[202:205], v[32:35]
	v_mfma_f32_16x16x32_bf16 v[20:23], v[144:147], v[210:213], v[20:23]
	v_mfma_f32_16x16x32_bf16 v[16:19], v[152:155], v[210:213], v[16:19]
	v_mfma_f32_16x16x32_bf16 v[60:63], v[148:151], v[180:183], v[60:63]
	v_mfma_f32_16x16x32_bf16 v[56:59], v[156:159], v[180:183], v[56:59]
	v_mfma_f32_16x16x32_bf16 v[52:55], v[148:151], v[188:191], v[52:55]
	v_mfma_f32_16x16x32_bf16 v[48:51], v[156:159], v[188:191], v[48:51]
	v_mfma_f32_16x16x32_bf16 v[36:39], v[148:151], v[206:209], v[36:39]
	v_mfma_f32_16x16x32_bf16 v[32:35], v[156:159], v[206:209], v[32:35]
	v_mfma_f32_16x16x32_bf16 v[20:23], v[148:151], v[214:217], v[20:23]
	v_mfma_f32_16x16x32_bf16 v[16:19], v[156:159], v[214:217], v[16:19]
	v_mfma_f32_16x16x32_bf16 v[44:47], v[160:163], v[176:179], v[44:47]
	v_mfma_f32_16x16x32_bf16 v[40:43], v[168:171], v[176:179], v[40:43]
	v_mfma_f32_16x16x32_bf16 v[28:31], v[160:163], v[184:187], v[28:31]
	v_mfma_f32_16x16x32_bf16 v[24:27], v[168:171], v[184:187], v[24:27]
	v_mfma_f32_16x16x32_bf16 v[12:15], v[160:163], v[202:205], v[12:15]
	v_mfma_f32_16x16x32_bf16 v[8:11], v[168:171], v[202:205], v[8:11]
	v_mfma_f32_16x16x32_bf16 v[4:7], v[160:163], v[210:213], v[4:7]
	v_mfma_f32_16x16x32_bf16 v[0:3], v[168:171], v[210:213], v[0:3]
	v_mfma_f32_16x16x32_bf16 v[44:47], v[164:167], v[180:183], v[44:47]
	v_mfma_f32_16x16x32_bf16 v[40:43], v[172:175], v[180:183], v[40:43]
	v_mfma_f32_16x16x32_bf16 v[28:31], v[164:167], v[188:191], v[28:31]
	v_mfma_f32_16x16x32_bf16 v[24:27], v[172:175], v[188:191], v[24:27]
	v_mfma_f32_16x16x32_bf16 v[12:15], v[164:167], v[206:209], v[12:15]
	v_mfma_f32_16x16x32_bf16 v[8:11], v[172:175], v[206:209], v[8:11]
	v_mfma_f32_16x16x32_bf16 v[4:7], v[164:167], v[214:217], v[4:7]
	v_mfma_f32_16x16x32_bf16 v[0:3], v[172:175], v[214:217], v[0:3]
	s_setprio 0
	s_barrier
	s_add_i32 s0, 0, 0x18000
	v_add_u32_e32 v143, s0, v140
	s_add_i32 s33, 0, 0x1c000
	ds_read_b128 v[144:147], v143
	ds_read_b128 v[148:151], v143 offset:1024
	ds_read_b128 v[152:155], v143 offset:2048
	ds_read_b128 v[156:159], v143 offset:3072
	v_add_u32_e32 v143, s33, v140
	ds_read_b128 v[160:163], v143
	ds_read_b128 v[164:167], v143 offset:1024
	ds_read_b128 v[168:171], v143 offset:2048
	ds_read_b128 v[172:175], v143 offset:3072
	s_add_u32 s14, s86, 0x40000
	s_addc_u32 s15, s87, 0
	s_mov_b32 m0, s53
	v_lshl_add_u64 v[228:229], s[14:15], 0, v[132:133]
	ds_read_b128 v[176:179], v142 offset:32768
	ds_read_b128 v[180:183], v142 offset:33792
	ds_read_b128 v[184:187], v142 offset:34816
	ds_read_b128 v[188:191], v142 offset:35840
	ds_read_b128 v[202:205], v142 offset:36864
	ds_read_b128 v[206:209], v142 offset:37888
	ds_read_b128 v[210:213], v142 offset:38912
	ds_read_b128 v[214:217], v142 offset:39936
	global_load_lds_dwordx4 v[228:229], off
	v_lshl_add_u64 v[228:229], s[14:15], 0, v[130:131]
	s_mov_b32 m0, s73
	s_nop 0
	global_load_lds_dwordx4 v[228:229], off
	s_waitcnt vmcnt(8)
	s_waitcnt lgkmcnt(0)
	s_barrier
	s_setprio 1
	s_waitcnt lgkmcnt(0)
	v_mfma_f32_16x16x32_bf16 v[124:127], v[144:147], v[176:179], v[124:127]
	v_mfma_f32_16x16x32_bf16 v[120:123], v[152:155], v[176:179], v[120:123]
	v_mfma_f32_16x16x32_bf16 v[116:119], v[144:147], v[184:187], v[116:119]
	v_mfma_f32_16x16x32_bf16 v[112:115], v[152:155], v[184:187], v[112:115]
	v_mfma_f32_16x16x32_bf16 v[100:103], v[144:147], v[202:205], v[100:103]
	v_mfma_f32_16x16x32_bf16 v[96:99], v[152:155], v[202:205], v[96:99]
	v_mfma_f32_16x16x32_bf16 v[84:87], v[144:147], v[210:213], v[84:87]
	v_mfma_f32_16x16x32_bf16 v[80:83], v[152:155], v[210:213], v[80:83]
	v_mfma_f32_16x16x32_bf16 v[124:127], v[148:151], v[180:183], v[124:127]
	v_mfma_f32_16x16x32_bf16 v[120:123], v[156:159], v[180:183], v[120:123]
	v_mfma_f32_16x16x32_bf16 v[116:119], v[148:151], v[188:191], v[116:119]
	v_mfma_f32_16x16x32_bf16 v[112:115], v[156:159], v[188:191], v[112:115]
	v_mfma_f32_16x16x32_bf16 v[100:103], v[148:151], v[206:209], v[100:103]
	v_mfma_f32_16x16x32_bf16 v[96:99], v[156:159], v[206:209], v[96:99]
	v_mfma_f32_16x16x32_bf16 v[84:87], v[148:151], v[214:217], v[84:87]
	v_mfma_f32_16x16x32_bf16 v[80:83], v[156:159], v[214:217], v[80:83]
	v_mfma_f32_16x16x32_bf16 v[108:111], v[160:163], v[176:179], v[108:111]
	v_mfma_f32_16x16x32_bf16 v[104:107], v[168:171], v[176:179], v[104:107]
	v_mfma_f32_16x16x32_bf16 v[92:95], v[160:163], v[184:187], v[92:95]
	v_mfma_f32_16x16x32_bf16 v[88:91], v[168:171], v[184:187], v[88:91]
	v_mfma_f32_16x16x32_bf16 v[76:79], v[160:163], v[202:205], v[76:79]
	v_mfma_f32_16x16x32_bf16 v[72:75], v[168:171], v[202:205], v[72:75]
	v_mfma_f32_16x16x32_bf16 v[68:71], v[160:163], v[210:213], v[68:71]
	v_mfma_f32_16x16x32_bf16 v[64:67], v[168:171], v[210:213], v[64:67]
	v_mfma_f32_16x16x32_bf16 v[108:111], v[164:167], v[180:183], v[108:111]
	v_mfma_f32_16x16x32_bf16 v[104:107], v[172:175], v[180:183], v[104:107]
	v_mfma_f32_16x16x32_bf16 v[92:95], v[164:167], v[188:191], v[92:95]
	v_mfma_f32_16x16x32_bf16 v[88:91], v[172:175], v[188:191], v[88:91]
	v_mfma_f32_16x16x32_bf16 v[76:79], v[164:167], v[206:209], v[76:79]
	v_mfma_f32_16x16x32_bf16 v[72:75], v[172:175], v[206:209], v[72:75]
	v_mfma_f32_16x16x32_bf16 v[68:71], v[164:167], v[214:217], v[68:71]
	v_mfma_f32_16x16x32_bf16 v[64:67], v[172:175], v[214:217], v[64:67]
	s_setprio 0
	s_barrier
	s_add_i32 s0, s0, s61
	v_lshl_add_u64 v[194:195], v[194:195], 0, s[40:41]
	s_mov_b32 m0, s0
	ds_read_b128 v[176:179], v142 offset:49152
	ds_read_b128 v[180:183], v142 offset:50176
	ds_read_b128 v[184:187], v142 offset:51200
	ds_read_b128 v[188:191], v142 offset:52224
	ds_read_b128 v[202:205], v142 offset:53248
	ds_read_b128 v[206:209], v142 offset:54272
	ds_read_b128 v[210:213], v142 offset:55296
	ds_read_b128 v[214:217], v142 offset:56320
	global_load_lds_dwordx4 v[194:195], off
	s_add_i32 m0, s0, 0x2000
	s_add_u32 s14, s84, 0x40080
	v_lshl_add_u64 v[194:195], v[196:197], 0, s[40:41]
	s_addc_u32 s15, s85, 0
	s_add_i32 s0, s33, s61
	global_load_lds_dwordx4 v[194:195], off
	v_lshl_add_u64 v[194:195], s[14:15], 0, v[192:193]
	s_mov_b32 m0, s0
	s_nop 0
	global_load_lds_dwordx4 v[194:195], off
	v_lshl_add_u64 v[194:195], s[14:15], 0, v[128:129]
	s_add_i32 m0, s0, 0x2000
	s_nop 0
	global_load_lds_dwordx4 v[194:195], off
	v_lshl_add_u64 v[194:195], v[218:219], 0, s[40:41]
	s_mov_b32 m0, s35
	s_nop 0
	global_load_lds_dwordx4 v[194:195], off
	v_lshl_add_u64 v[194:195], v[226:227], 0, s[40:41]
	s_mov_b32 m0, s46
	s_nop 0
	global_load_lds_dwordx4 v[194:195], off
	s_waitcnt vmcnt(8)
	s_waitcnt lgkmcnt(0)
	s_barrier
	s_setprio 1
	s_waitcnt lgkmcnt(0)
	v_mfma_f32_16x16x32_bf16 v[60:63], v[144:147], v[176:179], v[60:63]
	v_mfma_f32_16x16x32_bf16 v[56:59], v[152:155], v[176:179], v[56:59]
	v_mfma_f32_16x16x32_bf16 v[52:55], v[144:147], v[184:187], v[52:55]
	v_mfma_f32_16x16x32_bf16 v[48:51], v[152:155], v[184:187], v[48:51]
	v_mfma_f32_16x16x32_bf16 v[36:39], v[144:147], v[202:205], v[36:39]
	v_mfma_f32_16x16x32_bf16 v[32:35], v[152:155], v[202:205], v[32:35]
	v_mfma_f32_16x16x32_bf16 v[20:23], v[144:147], v[210:213], v[20:23]
	v_mfma_f32_16x16x32_bf16 v[16:19], v[152:155], v[210:213], v[16:19]
	v_mfma_f32_16x16x32_bf16 v[60:63], v[148:151], v[180:183], v[60:63]
	v_mfma_f32_16x16x32_bf16 v[56:59], v[156:159], v[180:183], v[56:59]
	v_mfma_f32_16x16x32_bf16 v[52:55], v[148:151], v[188:191], v[52:55]
	v_mfma_f32_16x16x32_bf16 v[48:51], v[156:159], v[188:191], v[48:51]
	v_mfma_f32_16x16x32_bf16 v[36:39], v[148:151], v[206:209], v[36:39]
	v_mfma_f32_16x16x32_bf16 v[32:35], v[156:159], v[206:209], v[32:35]
	v_mfma_f32_16x16x32_bf16 v[20:23], v[148:151], v[214:217], v[20:23]
	v_mfma_f32_16x16x32_bf16 v[16:19], v[156:159], v[214:217], v[16:19]
	v_mfma_f32_16x16x32_bf16 v[44:47], v[160:163], v[176:179], v[44:47]
	v_mfma_f32_16x16x32_bf16 v[40:43], v[168:171], v[176:179], v[40:43]
	v_mfma_f32_16x16x32_bf16 v[28:31], v[160:163], v[184:187], v[28:31]
	v_mfma_f32_16x16x32_bf16 v[24:27], v[168:171], v[184:187], v[24:27]
	v_mfma_f32_16x16x32_bf16 v[12:15], v[160:163], v[202:205], v[12:15]
	v_mfma_f32_16x16x32_bf16 v[8:11], v[168:171], v[202:205], v[8:11]
	v_mfma_f32_16x16x32_bf16 v[4:7], v[160:163], v[210:213], v[4:7]
	v_mfma_f32_16x16x32_bf16 v[0:3], v[168:171], v[210:213], v[0:3]
	v_mfma_f32_16x16x32_bf16 v[44:47], v[164:167], v[180:183], v[44:47]
	v_mfma_f32_16x16x32_bf16 v[40:43], v[172:175], v[180:183], v[40:43]
	v_mfma_f32_16x16x32_bf16 v[28:31], v[164:167], v[188:191], v[28:31]
	v_mfma_f32_16x16x32_bf16 v[24:27], v[172:175], v[188:191], v[24:27]
	v_mfma_f32_16x16x32_bf16 v[12:15], v[164:167], v[206:209], v[12:15]
	v_mfma_f32_16x16x32_bf16 v[8:11], v[172:175], v[206:209], v[8:11]
	v_mfma_f32_16x16x32_bf16 v[4:7], v[164:167], v[214:217], v[4:7]
	v_mfma_f32_16x16x32_bf16 v[0:3], v[172:175], v[214:217], v[0:3]
	s_setprio 0
	s_barrier
	s_add_i32 s93, s93, 2
	s_add_u32 s82, s82, 0x100
	s_addc_u32 s83, s83, 0
	s_add_u32 s90, s90, 0x100
	s_addc_u32 s91, s91, 0
	s_cmp_gt_u32 s93, 13
	s_cbranch_scc0 .LBB0_278
	s_and_b64 vcc, exec, s[20:21]
	s_cbranch_vccz .LBB0_281
	s_barrier

.LBB0_338:
	s_add_u32 s0, s66, 0xfffc0080
	s_addc_u32 s14, s67, -1
	s_add_i32 s15, 0, 0x10000
	s_cmp_eq_u32 s72, 12
	s_cselect_b32 s71, s23, s14
	s_cselect_b32 s70, s62, s0
	s_cselect_b32 s69, s1, s65
	s_cselect_b32 s68, s21, s64
	s_add_i32 s0, 0, 0x14000
	v_add_u32_e32 v154, s15, v139
	v_add_u32_e32 v170, s0, v139
	ds_read_b128 v[142:145], v154
	ds_read_b128 v[146:149], v154 offset:1024
	ds_read_b128 v[150:153], v154 offset:2048
	ds_read_b128 v[154:157], v154 offset:3072
	ds_read_b128 v[158:161], v170
	ds_read_b128 v[162:165], v170 offset:1024
	ds_read_b128 v[166:169], v170 offset:2048
	ds_read_b128 v[170:173], v170 offset:3072
	v_lshl_add_u64 v[190:191], s[66:67], 0, v[134:135]
	s_add_i32 m0, s19, 0xc000
	ds_read_b128 v[174:177], v141
	ds_read_b128 v[178:181], v141 offset:1024
	ds_read_b128 v[182:185], v141 offset:2048
	ds_read_b128 v[186:189], v141 offset:3072
	ds_read_b128 v[202:205], v141 offset:4096
	ds_read_b128 v[206:209], v141 offset:5120
	ds_read_b128 v[210:213], v141 offset:6144
	ds_read_b128 v[214:217], v141 offset:7168
	global_load_lds_dwordx4 v[190:191], off
	v_lshl_add_u64 v[190:191], s[66:67], 0, v[136:137]
	s_add_i32 m0, s19, 0xe000
	s_nop 0
	global_load_lds_dwordx4 v[190:191], off
	s_waitcnt vmcnt(8)
	s_waitcnt lgkmcnt(0)
	s_barrier
	s_setprio 1
	s_waitcnt lgkmcnt(0)
	v_mfma_f32_16x16x32_bf16 v[124:127], v[142:145], v[174:177], v[124:127]
	v_mfma_f32_16x16x32_bf16 v[120:123], v[150:153], v[174:177], v[120:123]
	v_mfma_f32_16x16x32_bf16 v[116:119], v[142:145], v[182:185], v[116:119]
	v_mfma_f32_16x16x32_bf16 v[112:115], v[150:153], v[182:185], v[112:115]
	v_mfma_f32_16x16x32_bf16 v[100:103], v[142:145], v[202:205], v[100:103]
	v_mfma_f32_16x16x32_bf16 v[96:99], v[150:153], v[202:205], v[96:99]
	v_mfma_f32_16x16x32_bf16 v[84:87], v[142:145], v[210:213], v[84:87]
	v_mfma_f32_16x16x32_bf16 v[80:83], v[150:153], v[210:213], v[80:83]
	v_mfma_f32_16x16x32_bf16 v[124:127], v[146:149], v[178:181], v[124:127]
	v_mfma_f32_16x16x32_bf16 v[120:123], v[154:157], v[178:181], v[120:123]
	v_mfma_f32_16x16x32_bf16 v[116:119], v[146:149], v[186:189], v[116:119]
	v_mfma_f32_16x16x32_bf16 v[112:115], v[154:157], v[186:189], v[112:115]
	v_mfma_f32_16x16x32_bf16 v[100:103], v[146:149], v[206:209], v[100:103]
	v_mfma_f32_16x16x32_bf16 v[96:99], v[154:157], v[206:209], v[96:99]
	v_mfma_f32_16x16x32_bf16 v[84:87], v[146:149], v[214:217], v[84:87]
	v_mfma_f32_16x16x32_bf16 v[80:83], v[154:157], v[214:217], v[80:83]
	v_mfma_f32_16x16x32_bf16 v[108:111], v[158:161], v[174:177], v[108:111]
	v_mfma_f32_16x16x32_bf16 v[104:107], v[166:169], v[174:177], v[104:107]
	v_mfma_f32_16x16x32_bf16 v[92:95], v[158:161], v[182:185], v[92:95]
	v_mfma_f32_16x16x32_bf16 v[88:91], v[166:169], v[182:185], v[88:91]
	v_mfma_f32_16x16x32_bf16 v[76:79], v[158:161], v[202:205], v[76:79]
	v_mfma_f32_16x16x32_bf16 v[72:75], v[166:169], v[202:205], v[72:75]
	v_mfma_f32_16x16x32_bf16 v[68:71], v[158:161], v[210:213], v[68:71]
	v_mfma_f32_16x16x32_bf16 v[64:67], v[166:169], v[210:213], v[64:67]
	v_mfma_f32_16x16x32_bf16 v[108:111], v[162:165], v[178:181], v[108:111]
	v_mfma_f32_16x16x32_bf16 v[104:107], v[170:173], v[178:181], v[104:107]
	v_mfma_f32_16x16x32_bf16 v[92:95], v[162:165], v[186:189], v[92:95]
	v_mfma_f32_16x16x32_bf16 v[88:91], v[170:173], v[186:189], v[88:91]
	v_mfma_f32_16x16x32_bf16 v[76:79], v[162:165], v[206:209], v[76:79]
	v_mfma_f32_16x16x32_bf16 v[72:75], v[170:173], v[206:209], v[72:75]
	v_mfma_f32_16x16x32_bf16 v[68:71], v[162:165], v[214:217], v[68:71]
	v_mfma_f32_16x16x32_bf16 v[64:67], v[170:173], v[214:217], v[64:67]
	s_setprio 0
	s_barrier
	s_add_i32 s14, s15, s29
	v_lshl_add_u64 v[190:191], s[68:69], 0, v[192:193]
	s_mov_b32 m0, s14
	ds_read_b128 v[174:177], v141 offset:16384
	ds_read_b128 v[178:181], v141 offset:17408
	ds_read_b128 v[182:185], v141 offset:18432
	ds_read_b128 v[186:189], v141 offset:19456
	ds_read_b128 v[202:205], v141 offset:20480
	ds_read_b128 v[206:209], v141 offset:21504
	ds_read_b128 v[210:213], v141 offset:22528
	ds_read_b128 v[214:217], v141 offset:23552
	global_load_lds_dwordx4 v[190:191], off
	s_add_i32 m0, s14, 0x2000
	s_add_u32 s14, s68, 0x40000
	v_lshl_add_u64 v[194:195], s[68:69], 0, v[128:129]
	s_addc_u32 s15, s69, 0
	s_add_i32 s0, s0, s29
	global_load_lds_dwordx4 v[194:195], off
	v_lshl_add_u64 v[196:197], s[14:15], 0, v[192:193]
	s_mov_b32 m0, s0
	v_lshl_add_u64 v[218:219], s[70:71], 0, v[130:131]
	global_load_lds_dwordx4 v[196:197], off
	v_lshl_add_u64 v[196:197], s[14:15], 0, v[128:129]
	s_add_i32 m0, s0, 0x2000
	s_nop 0
	global_load_lds_dwordx4 v[196:197], off
	v_lshl_add_u64 v[196:197], s[70:71], 0, v[132:133]
	s_mov_b32 m0, s19
	s_nop 0
	global_load_lds_dwordx4 v[196:197], off
	s_mov_b32 m0, s48
	s_nop 0
	global_load_lds_dwordx4 v[218:219], off
	s_waitcnt vmcnt(8)
	s_waitcnt lgkmcnt(0)
	s_barrier
	s_setprio 1
	s_waitcnt lgkmcnt(0)
	v_mfma_f32_16x16x32_bf16 v[60:63], v[142:145], v[174:177], v[60:63]
	v_mfma_f32_16x16x32_bf16 v[56:59], v[150:153], v[174:177], v[56:59]
	v_mfma_f32_16x16x32_bf16 v[52:55], v[142:145], v[182:185], v[52:55]
	v_mfma_f32_16x16x32_bf16 v[48:51], v[150:153], v[182:185], v[48:51]
	v_mfma_f32_16x16x32_bf16 v[36:39], v[142:145], v[202:205], v[36:39]
	v_mfma_f32_16x16x32_bf16 v[32:35], v[150:153], v[202:205], v[32:35]
	v_mfma_f32_16x16x32_bf16 v[20:23], v[142:145], v[210:213], v[20:23]
	v_mfma_f32_16x16x32_bf16 v[16:19], v[150:153], v[210:213], v[16:19]
	v_mfma_f32_16x16x32_bf16 v[60:63], v[146:149], v[178:181], v[60:63]
	v_mfma_f32_16x16x32_bf16 v[56:59], v[154:157], v[178:181], v[56:59]
	v_mfma_f32_16x16x32_bf16 v[52:55], v[146:149], v[186:189], v[52:55]
	v_mfma_f32_16x16x32_bf16 v[48:51], v[154:157], v[186:189], v[48:51]
	v_mfma_f32_16x16x32_bf16 v[36:39], v[146:149], v[206:209], v[36:39]
	v_mfma_f32_16x16x32_bf16 v[32:35], v[154:157], v[206:209], v[32:35]
	v_mfma_f32_16x16x32_bf16 v[20:23], v[146:149], v[214:217], v[20:23]
	v_mfma_f32_16x16x32_bf16 v[16:19], v[154:157], v[214:217], v[16:19]
	v_mfma_f32_16x16x32_bf16 v[44:47], v[158:161], v[174:177], v[44:47]
	v_mfma_f32_16x16x32_bf16 v[40:43], v[166:169], v[174:177], v[40:43]
	v_mfma_f32_16x16x32_bf16 v[28:31], v[158:161], v[182:185], v[28:31]
	v_mfma_f32_16x16x32_bf16 v[24:27], v[166:169], v[182:185], v[24:27]
	v_mfma_f32_16x16x32_bf16 v[12:15], v[158:161], v[202:205], v[12:15]
	v_mfma_f32_16x16x32_bf16 v[8:11], v[166:169], v[202:205], v[8:11]
	v_mfma_f32_16x16x32_bf16 v[4:7], v[158:161], v[210:213], v[4:7]
	v_mfma_f32_16x16x32_bf16 v[0:3], v[166:169], v[210:213], v[0:3]
	v_mfma_f32_16x16x32_bf16 v[44:47], v[162:165], v[178:181], v[44:47]
	v_mfma_f32_16x16x32_bf16 v[40:43], v[170:173], v[178:181], v[40:43]
	v_mfma_f32_16x16x32_bf16 v[28:31], v[162:165], v[186:189], v[28:31]
	v_mfma_f32_16x16x32_bf16 v[24:27], v[170:173], v[186:189], v[24:27]
	v_mfma_f32_16x16x32_bf16 v[12:15], v[162:165], v[206:209], v[12:15]
	v_mfma_f32_16x16x32_bf16 v[8:11], v[170:173], v[206:209], v[8:11]
	v_mfma_f32_16x16x32_bf16 v[4:7], v[162:165], v[214:217], v[4:7]
	v_mfma_f32_16x16x32_bf16 v[0:3], v[170:173], v[214:217], v[0:3]
	s_setprio 0
	s_barrier
	s_add_i32 s0, 0, 0x18000
	s_add_i32 s33, 0, 0x1c000
	v_add_u32_e32 v154, s0, v139
	v_add_u32_e32 v170, s33, v139
	ds_read_b128 v[142:145], v154
	ds_read_b128 v[146:149], v154 offset:1024
	ds_read_b128 v[150:153], v154 offset:2048
	ds_read_b128 v[154:157], v154 offset:3072
	ds_read_b128 v[158:161], v170
	ds_read_b128 v[162:165], v170 offset:1024
	ds_read_b128 v[166:169], v170 offset:2048
	ds_read_b128 v[170:173], v170 offset:3072
	s_add_u32 s14, s70, 0x40000
	s_addc_u32 s15, s71, 0
	s_mov_b32 m0, s49
	v_lshl_add_u64 v[226:227], s[14:15], 0, v[132:133]
	ds_read_b128 v[174:177], v141 offset:32768
	ds_read_b128 v[178:181], v141 offset:33792
	ds_read_b128 v[182:185], v141 offset:34816
	ds_read_b128 v[186:189], v141 offset:35840
	ds_read_b128 v[202:205], v141 offset:36864
	ds_read_b128 v[206:209], v141 offset:37888
	ds_read_b128 v[210:213], v141 offset:38912
	ds_read_b128 v[214:217], v141 offset:39936
	global_load_lds_dwordx4 v[226:227], off
	v_lshl_add_u64 v[226:227], s[14:15], 0, v[130:131]
	s_mov_b32 m0, s46
	s_nop 0
	global_load_lds_dwordx4 v[226:227], off
	s_waitcnt vmcnt(8)
	s_waitcnt lgkmcnt(0)
	s_barrier
	s_setprio 1
	s_waitcnt lgkmcnt(0)
	v_mfma_f32_16x16x32_bf16 v[124:127], v[142:145], v[174:177], v[124:127]
	v_mfma_f32_16x16x32_bf16 v[120:123], v[150:153], v[174:177], v[120:123]
	v_mfma_f32_16x16x32_bf16 v[116:119], v[142:145], v[182:185], v[116:119]
	v_mfma_f32_16x16x32_bf16 v[112:115], v[150:153], v[182:185], v[112:115]
	v_mfma_f32_16x16x32_bf16 v[100:103], v[142:145], v[202:205], v[100:103]
	v_mfma_f32_16x16x32_bf16 v[96:99], v[150:153], v[202:205], v[96:99]
	v_mfma_f32_16x16x32_bf16 v[84:87], v[142:145], v[210:213], v[84:87]
	v_mfma_f32_16x16x32_bf16 v[80:83], v[150:153], v[210:213], v[80:83]
	v_mfma_f32_16x16x32_bf16 v[124:127], v[146:149], v[178:181], v[124:127]
	v_mfma_f32_16x16x32_bf16 v[120:123], v[154:157], v[178:181], v[120:123]
	v_mfma_f32_16x16x32_bf16 v[116:119], v[146:149], v[186:189], v[116:119]
	v_mfma_f32_16x16x32_bf16 v[112:115], v[154:157], v[186:189], v[112:115]
	v_mfma_f32_16x16x32_bf16 v[100:103], v[146:149], v[206:209], v[100:103]
	v_mfma_f32_16x16x32_bf16 v[96:99], v[154:157], v[206:209], v[96:99]
	v_mfma_f32_16x16x32_bf16 v[84:87], v[146:149], v[214:217], v[84:87]
	v_mfma_f32_16x16x32_bf16 v[80:83], v[154:157], v[214:217], v[80:83]
	v_mfma_f32_16x16x32_bf16 v[108:111], v[158:161], v[174:177], v[108:111]
	v_mfma_f32_16x16x32_bf16 v[104:107], v[166:169], v[174:177], v[104:107]
	v_mfma_f32_16x16x32_bf16 v[92:95], v[158:161], v[182:185], v[92:95]
	v_mfma_f32_16x16x32_bf16 v[88:91], v[166:169], v[182:185], v[88:91]
	v_mfma_f32_16x16x32_bf16 v[76:79], v[158:161], v[202:205], v[76:79]
	v_mfma_f32_16x16x32_bf16 v[72:75], v[166:169], v[202:205], v[72:75]
	v_mfma_f32_16x16x32_bf16 v[68:71], v[158:161], v[210:213], v[68:71]
	v_mfma_f32_16x16x32_bf16 v[64:67], v[166:169], v[210:213], v[64:67]
	v_mfma_f32_16x16x32_bf16 v[108:111], v[162:165], v[178:181], v[108:111]
	v_mfma_f32_16x16x32_bf16 v[104:107], v[170:173], v[178:181], v[104:107]
	v_mfma_f32_16x16x32_bf16 v[92:95], v[162:165], v[186:189], v[92:95]
	v_mfma_f32_16x16x32_bf16 v[88:91], v[170:173], v[186:189], v[88:91]
	v_mfma_f32_16x16x32_bf16 v[76:79], v[162:165], v[206:209], v[76:79]
	v_mfma_f32_16x16x32_bf16 v[72:75], v[170:173], v[206:209], v[72:75]
	v_mfma_f32_16x16x32_bf16 v[68:71], v[162:165], v[214:217], v[68:71]
	v_mfma_f32_16x16x32_bf16 v[64:67], v[170:173], v[214:217], v[64:67]
	s_setprio 0
	s_barrier
	s_add_i32 s0, s0, s29
	v_lshl_add_u64 v[190:191], v[190:191], 0, s[40:41]
	s_mov_b32 m0, s0
	ds_read_b128 v[174:177], v141 offset:49152
	ds_read_b128 v[178:181], v141 offset:50176
	ds_read_b128 v[182:185], v141 offset:51200
	ds_read_b128 v[186:189], v141 offset:52224
	ds_read_b128 v[202:205], v141 offset:53248
	ds_read_b128 v[206:209], v141 offset:54272
	ds_read_b128 v[210:213], v141 offset:55296
	ds_read_b128 v[214:217], v141 offset:56320
	global_load_lds_dwordx4 v[190:191], off
	s_add_i32 m0, s0, 0x2000
	s_add_u32 s14, s68, 0x40080
	v_lshl_add_u64 v[190:191], v[194:195], 0, s[40:41]
	s_addc_u32 s15, s69, 0
	s_add_i32 s0, s33, s29
	global_load_lds_dwordx4 v[190:191], off
	v_lshl_add_u64 v[190:191], s[14:15], 0, v[192:193]
	s_mov_b32 m0, s0
	s_nop 0
	global_load_lds_dwordx4 v[190:191], off
	v_lshl_add_u64 v[190:191], s[14:15], 0, v[128:129]
	s_add_i32 m0, s0, 0x2000
	s_nop 0
	global_load_lds_dwordx4 v[190:191], off
	v_lshl_add_u64 v[190:191], v[196:197], 0, s[40:41]
	s_mov_b32 m0, s52
	s_nop 0
	global_load_lds_dwordx4 v[190:191], off
	v_lshl_add_u64 v[190:191], v[218:219], 0, s[40:41]
	s_mov_b32 m0, s53
	s_nop 0
	global_load_lds_dwordx4 v[190:191], off
	s_waitcnt vmcnt(8)
	s_waitcnt lgkmcnt(0)
	s_barrier
	s_setprio 1
	s_waitcnt lgkmcnt(0)
	v_mfma_f32_16x16x32_bf16 v[60:63], v[142:145], v[174:177], v[60:63]
	v_mfma_f32_16x16x32_bf16 v[56:59], v[150:153], v[174:177], v[56:59]
	v_mfma_f32_16x16x32_bf16 v[52:55], v[142:145], v[182:185], v[52:55]
	v_mfma_f32_16x16x32_bf16 v[48:51], v[150:153], v[182:185], v[48:51]
	v_mfma_f32_16x16x32_bf16 v[36:39], v[142:145], v[202:205], v[36:39]
	v_mfma_f32_16x16x32_bf16 v[32:35], v[150:153], v[202:205], v[32:35]
	v_mfma_f32_16x16x32_bf16 v[20:23], v[142:145], v[210:213], v[20:23]
	v_mfma_f32_16x16x32_bf16 v[16:19], v[150:153], v[210:213], v[16:19]
	v_mfma_f32_16x16x32_bf16 v[60:63], v[146:149], v[178:181], v[60:63]
	v_mfma_f32_16x16x32_bf16 v[56:59], v[154:157], v[178:181], v[56:59]
	v_mfma_f32_16x16x32_bf16 v[52:55], v[146:149], v[186:189], v[52:55]
	v_mfma_f32_16x16x32_bf16 v[48:51], v[154:157], v[186:189], v[48:51]
	v_mfma_f32_16x16x32_bf16 v[36:39], v[146:149], v[206:209], v[36:39]
	v_mfma_f32_16x16x32_bf16 v[32:35], v[154:157], v[206:209], v[32:35]
	v_mfma_f32_16x16x32_bf16 v[20:23], v[146:149], v[214:217], v[20:23]
	v_mfma_f32_16x16x32_bf16 v[16:19], v[154:157], v[214:217], v[16:19]
	v_mfma_f32_16x16x32_bf16 v[44:47], v[158:161], v[174:177], v[44:47]
	v_mfma_f32_16x16x32_bf16 v[40:43], v[166:169], v[174:177], v[40:43]
	v_mfma_f32_16x16x32_bf16 v[28:31], v[158:161], v[182:185], v[28:31]
	v_mfma_f32_16x16x32_bf16 v[24:27], v[166:169], v[182:185], v[24:27]
	v_mfma_f32_16x16x32_bf16 v[12:15], v[158:161], v[202:205], v[12:15]
	v_mfma_f32_16x16x32_bf16 v[8:11], v[166:169], v[202:205], v[8:11]
	v_mfma_f32_16x16x32_bf16 v[4:7], v[158:161], v[210:213], v[4:7]
	v_mfma_f32_16x16x32_bf16 v[0:3], v[166:169], v[210:213], v[0:3]
	v_mfma_f32_16x16x32_bf16 v[44:47], v[162:165], v[178:181], v[44:47]
	v_mfma_f32_16x16x32_bf16 v[40:43], v[170:173], v[178:181], v[40:43]
	v_mfma_f32_16x16x32_bf16 v[28:31], v[162:165], v[186:189], v[28:31]
	v_mfma_f32_16x16x32_bf16 v[24:27], v[170:173], v[186:189], v[24:27]
	v_mfma_f32_16x16x32_bf16 v[12:15], v[162:165], v[206:209], v[12:15]
	v_mfma_f32_16x16x32_bf16 v[8:11], v[170:173], v[206:209], v[8:11]
	v_mfma_f32_16x16x32_bf16 v[4:7], v[162:165], v[214:217], v[4:7]
	v_mfma_f32_16x16x32_bf16 v[0:3], v[170:173], v[214:217], v[0:3]
	s_setprio 0
	s_barrier
	s_add_i32 s72, s72, 2
	s_add_u32 s66, s66, 0x100
	s_addc_u32 s67, s67, 0
	s_add_u32 s64, s64, 0x100
	s_addc_u32 s65, s65, 0
	s_cmp_gt_u32 s72, 13
	s_cbranch_scc0 .LBB0_338
	s_and_b64 vcc, exec, s[16:17]
	s_cbranch_vccz .LBB0_341
	s_barrier
